# GEMM main loops: per-cluster s_setprio 1/0 flips removed (no VALU besides the MFMAs is left in the loops for the priority to arbitrate)
# speedup vs baseline: 1.0324x; 1.0080x over previous
.LBB0_227:
	s_add_u32 s22, s20, 0xfff80080
	s_addc_u32 s23, s21, -1
	s_add_i32 s59, 0, 0x10000
	ds_read_b128 v[140:143], v234
	ds_read_b128 v[144:147], v234 offset:1024
	ds_read_b128 v[148:151], v234 offset:2048
	ds_read_b128 v[170:173], v234 offset:3072
	s_cmp_eq_u32 s58, 28
	s_cselect_b32 s43, s5, s23
	s_cselect_b32 s42, s6, s22
	s_cselect_b32 s23, s7, s57
	s_cselect_b32 s22, s25, s35
	s_add_i32 m0, s49, 0xc000
	ds_read_b128 v[174:177], v168
	ds_read_b128 v[178:181], v168 offset:1024
	ds_read_b128 v[182:185], v168 offset:2048
	ds_read_b128 v[186:189], v168 offset:3072
	ds_read_b128 v[190:193], v168 offset:4096
	ds_read_b128 v[206:209], v168 offset:5120
	ds_read_b128 v[210:213], v168 offset:6144
	ds_read_b128 v[214:217], v168 offset:7168
	global_load_lds_dwordx4 v136, s[20:21]
	s_add_i32 m0, s49, 0xe000
	s_nop 0
	global_load_lds_dwordx4 v138, s[20:21]
	s_waitcnt lgkmcnt(8)
	s_barrier
	s_waitcnt lgkmcnt(0)
	v_mfma_f32_16x16x32_bf16 v[124:127], v[140:143], v[174:177], v[124:127]
	v_mfma_f32_16x16x32_bf16 v[120:123], v[148:151], v[174:177], v[120:123]
	v_mfma_f32_16x16x32_bf16 v[108:111], v[140:143], v[182:185], v[108:111]
	v_mfma_f32_16x16x32_bf16 v[104:107], v[148:151], v[182:185], v[104:107]
	v_mfma_f32_16x16x32_bf16 v[92:95], v[140:143], v[190:193], v[92:95]
	v_mfma_f32_16x16x32_bf16 v[88:91], v[148:151], v[190:193], v[88:91]
	v_mfma_f32_16x16x32_bf16 v[76:79], v[140:143], v[210:213], v[76:79]
	v_mfma_f32_16x16x32_bf16 v[72:75], v[148:151], v[210:213], v[72:75]
	v_mfma_f32_16x16x32_bf16 v[124:127], v[144:147], v[178:181], v[124:127]
	v_mfma_f32_16x16x32_bf16 v[120:123], v[170:173], v[178:181], v[120:123]
	v_mfma_f32_16x16x32_bf16 v[108:111], v[144:147], v[186:189], v[108:111]
	v_mfma_f32_16x16x32_bf16 v[104:107], v[170:173], v[186:189], v[104:107]
	v_mfma_f32_16x16x32_bf16 v[92:95], v[144:147], v[206:209], v[92:95]
	v_mfma_f32_16x16x32_bf16 v[88:91], v[170:173], v[206:209], v[88:91]
	v_mfma_f32_16x16x32_bf16 v[76:79], v[144:147], v[214:217], v[76:79]
	v_mfma_f32_16x16x32_bf16 v[72:75], v[170:173], v[214:217], v[72:75]
	s_barrier
	s_add_i32 s62, 0, 0x14000
	s_add_i32 s59, s59, s48
	s_mov_b32 m0, s59
	ds_read_b128 v[218:221], v235
	ds_read_b128 v[222:225], v235 offset:1024
	ds_read_b128 v[226:229], v235 offset:2048
	ds_read_b128 v[230:233], v235 offset:3072
	global_load_lds_dwordx4 v130, s[22:23]
	s_add_i32 m0, s59, 0x2000
	s_nop 0
	global_load_lds_dwordx4 v134, s[22:23]
	s_barrier
	s_waitcnt lgkmcnt(0)
	v_mfma_f32_16x16x32_bf16 v[116:119], v[218:221], v[174:177], v[116:119]
	v_mfma_f32_16x16x32_bf16 v[112:115], v[226:229], v[174:177], v[112:115]
	v_mfma_f32_16x16x32_bf16 v[100:103], v[218:221], v[182:185], v[100:103]
	v_mfma_f32_16x16x32_bf16 v[96:99], v[226:229], v[182:185], v[96:99]
	v_mfma_f32_16x16x32_bf16 v[84:87], v[218:221], v[190:193], v[84:87]
	v_mfma_f32_16x16x32_bf16 v[80:83], v[226:229], v[190:193], v[80:83]
	v_mfma_f32_16x16x32_bf16 v[68:71], v[218:221], v[210:213], v[68:71]
	v_mfma_f32_16x16x32_bf16 v[64:67], v[226:229], v[210:213], v[64:67]
	v_mfma_f32_16x16x32_bf16 v[116:119], v[222:225], v[178:181], v[116:119]
	v_mfma_f32_16x16x32_bf16 v[112:115], v[230:233], v[178:181], v[112:115]
	v_mfma_f32_16x16x32_bf16 v[100:103], v[222:225], v[186:189], v[100:103]
	v_mfma_f32_16x16x32_bf16 v[96:99], v[230:233], v[186:189], v[96:99]
	v_mfma_f32_16x16x32_bf16 v[84:87], v[222:225], v[206:209], v[84:87]
	v_mfma_f32_16x16x32_bf16 v[80:83], v[230:233], v[206:209], v[80:83]
	v_mfma_f32_16x16x32_bf16 v[68:71], v[222:225], v[214:217], v[68:71]
	v_mfma_f32_16x16x32_bf16 v[64:67], v[230:233], v[214:217], v[64:67]
	s_mov_b32 m0, s49
	s_add_u32 s98, s42, 0x80
	s_addc_u32 s99, s43, 0
	s_barrier
	ds_read_b128 v[174:177], v168 offset:16384
	ds_read_b128 v[178:181], v168 offset:17408
	ds_read_b128 v[182:185], v168 offset:18432
	ds_read_b128 v[186:189], v168 offset:19456
	ds_read_b128 v[190:193], v168 offset:20480
	ds_read_b128 v[206:209], v168 offset:21504
	ds_read_b128 v[210:213], v168 offset:22528
	ds_read_b128 v[214:217], v168 offset:23552
	global_load_lds_dwordx4 v128, s[42:43]
	s_mov_b32 m0, s50
	s_nop 0
	global_load_lds_dwordx4 v132, s[42:43]
	s_barrier
	s_waitcnt lgkmcnt(0)
	v_mfma_f32_16x16x32_bf16 v[60:63], v[140:143], v[174:177], v[60:63]
	v_mfma_f32_16x16x32_bf16 v[56:59], v[148:151], v[174:177], v[56:59]
	v_mfma_f32_16x16x32_bf16 v[48:51], v[140:143], v[182:185], v[48:51]
	v_mfma_f32_16x16x32_bf16 v[40:43], v[148:151], v[182:185], v[40:43]
	v_mfma_f32_16x16x32_bf16 v[32:35], v[140:143], v[190:193], v[32:35]
	v_mfma_f32_16x16x32_bf16 v[24:27], v[148:151], v[190:193], v[24:27]
	v_mfma_f32_16x16x32_bf16 v[16:19], v[140:143], v[210:213], v[16:19]
	v_mfma_f32_16x16x32_bf16 v[8:11], v[148:151], v[210:213], v[8:11]
	v_mfma_f32_16x16x32_bf16 v[60:63], v[144:147], v[178:181], v[60:63]
	v_mfma_f32_16x16x32_bf16 v[56:59], v[170:173], v[178:181], v[56:59]
	v_mfma_f32_16x16x32_bf16 v[48:51], v[144:147], v[186:189], v[48:51]
	v_mfma_f32_16x16x32_bf16 v[40:43], v[170:173], v[186:189], v[40:43]
	v_mfma_f32_16x16x32_bf16 v[32:35], v[144:147], v[206:209], v[32:35]
	v_mfma_f32_16x16x32_bf16 v[24:27], v[170:173], v[206:209], v[24:27]
	v_mfma_f32_16x16x32_bf16 v[16:19], v[144:147], v[214:217], v[16:19]
	v_mfma_f32_16x16x32_bf16 v[8:11], v[170:173], v[214:217], v[8:11]
	s_barrier
	s_add_u32 s60, s22, 0x80000
	s_addc_u32 s61, s23, 0
	s_add_i32 s59, s62, s48
	s_mov_b32 m0, s59
	s_nop 0
	global_load_lds_dwordx4 v130, s[60:61]
	s_add_i32 m0, s59, 0x2000
	s_nop 0
	global_load_lds_dwordx4 v134, s[60:61]
	s_waitcnt vmcnt(6)
	s_barrier
	v_mfma_f32_16x16x32_bf16 v[52:55], v[218:221], v[174:177], v[52:55]
	v_mfma_f32_16x16x32_bf16 v[44:47], v[226:229], v[174:177], v[44:47]
	v_mfma_f32_16x16x32_bf16 v[36:39], v[218:221], v[182:185], v[36:39]
	v_mfma_f32_16x16x32_bf16 v[28:31], v[226:229], v[182:185], v[28:31]
	v_mfma_f32_16x16x32_bf16 v[20:23], v[218:221], v[190:193], v[20:23]
	v_mfma_f32_16x16x32_bf16 v[12:15], v[226:229], v[190:193], v[12:15]
	v_mfma_f32_16x16x32_bf16 v[4:7], v[218:221], v[210:213], v[4:7]
	v_mfma_f32_16x16x32_bf16 v[0:3], v[226:229], v[210:213], v[0:3]
	v_mfma_f32_16x16x32_bf16 v[52:55], v[222:225], v[178:181], v[52:55]
	v_mfma_f32_16x16x32_bf16 v[44:47], v[230:233], v[178:181], v[44:47]
	v_mfma_f32_16x16x32_bf16 v[36:39], v[222:225], v[186:189], v[36:39]
	v_mfma_f32_16x16x32_bf16 v[28:31], v[230:233], v[186:189], v[28:31]
	v_mfma_f32_16x16x32_bf16 v[20:23], v[222:225], v[206:209], v[20:23]
	v_mfma_f32_16x16x32_bf16 v[12:15], v[230:233], v[206:209], v[12:15]
	v_mfma_f32_16x16x32_bf16 v[4:7], v[222:225], v[214:217], v[4:7]
	v_mfma_f32_16x16x32_bf16 v[0:3], v[230:233], v[214:217], v[0:3]
	s_add_i32 s59, 0, 0x18000
	s_barrier
	ds_read_b128 v[140:143], v236
	ds_read_b128 v[144:147], v236 offset:1024
	ds_read_b128 v[148:151], v236 offset:2048
	ds_read_b128 v[170:173], v236 offset:3072
	s_add_u32 s42, s42, 0x80000
	s_addc_u32 s43, s43, 0
	s_mov_b32 m0, s51
	ds_read_b128 v[174:177], v168 offset:32768
	ds_read_b128 v[178:181], v168 offset:33792
	ds_read_b128 v[182:185], v168 offset:34816
	ds_read_b128 v[186:189], v168 offset:35840
	ds_read_b128 v[190:193], v168 offset:36864
	ds_read_b128 v[206:209], v168 offset:37888
	ds_read_b128 v[210:213], v168 offset:38912
	ds_read_b128 v[214:217], v168 offset:39936
	global_load_lds_dwordx4 v128, s[42:43]
	s_mov_b32 m0, s52
	s_nop 0
	global_load_lds_dwordx4 v132, s[42:43]
	s_waitcnt lgkmcnt(8)
	s_barrier
	s_waitcnt lgkmcnt(0)
	v_mfma_f32_16x16x32_bf16 v[124:127], v[140:143], v[174:177], v[124:127]
	v_mfma_f32_16x16x32_bf16 v[120:123], v[148:151], v[174:177], v[120:123]
	v_mfma_f32_16x16x32_bf16 v[108:111], v[140:143], v[182:185], v[108:111]
	v_mfma_f32_16x16x32_bf16 v[104:107], v[148:151], v[182:185], v[104:107]
	v_mfma_f32_16x16x32_bf16 v[92:95], v[140:143], v[190:193], v[92:95]
	v_mfma_f32_16x16x32_bf16 v[88:91], v[148:151], v[190:193], v[88:91]
	v_mfma_f32_16x16x32_bf16 v[76:79], v[140:143], v[210:213], v[76:79]
	v_mfma_f32_16x16x32_bf16 v[72:75], v[148:151], v[210:213], v[72:75]
	v_mfma_f32_16x16x32_bf16 v[124:127], v[144:147], v[178:181], v[124:127]
	v_mfma_f32_16x16x32_bf16 v[120:123], v[170:173], v[178:181], v[120:123]
	v_mfma_f32_16x16x32_bf16 v[108:111], v[144:147], v[186:189], v[108:111]
	v_mfma_f32_16x16x32_bf16 v[104:107], v[170:173], v[186:189], v[104:107]
	v_mfma_f32_16x16x32_bf16 v[92:95], v[144:147], v[206:209], v[92:95]
	v_mfma_f32_16x16x32_bf16 v[88:91], v[170:173], v[206:209], v[88:91]
	v_mfma_f32_16x16x32_bf16 v[76:79], v[144:147], v[214:217], v[76:79]
	v_mfma_f32_16x16x32_bf16 v[72:75], v[170:173], v[214:217], v[72:75]
	s_barrier
	s_add_i32 s42, 0, 0x1c000
	s_add_i32 s43, s59, s48
	s_add_u32 s100, s22, 0x80
	s_addc_u32 s101, s23, 0
	s_mov_b32 m0, s43
	ds_read_b128 v[218:221], v237
	ds_read_b128 v[222:225], v237 offset:1024
	ds_read_b128 v[226:229], v237 offset:2048
	ds_read_b128 v[230:233], v237 offset:3072
	global_load_lds_dwordx4 v130, s[100:101]
	s_add_i32 m0, s43, 0x2000
	s_nop 0
	global_load_lds_dwordx4 v134, s[100:101]
	s_barrier
	s_waitcnt lgkmcnt(0)
	v_mfma_f32_16x16x32_bf16 v[116:119], v[218:221], v[174:177], v[116:119]
	v_mfma_f32_16x16x32_bf16 v[112:115], v[226:229], v[174:177], v[112:115]
	v_mfma_f32_16x16x32_bf16 v[100:103], v[218:221], v[182:185], v[100:103]
	v_mfma_f32_16x16x32_bf16 v[96:99], v[226:229], v[182:185], v[96:99]
	v_mfma_f32_16x16x32_bf16 v[84:87], v[218:221], v[190:193], v[84:87]
	v_mfma_f32_16x16x32_bf16 v[80:83], v[226:229], v[190:193], v[80:83]
	v_mfma_f32_16x16x32_bf16 v[68:71], v[218:221], v[210:213], v[68:71]
	v_mfma_f32_16x16x32_bf16 v[64:67], v[226:229], v[210:213], v[64:67]
	v_mfma_f32_16x16x32_bf16 v[116:119], v[222:225], v[178:181], v[116:119]
	v_mfma_f32_16x16x32_bf16 v[112:115], v[230:233], v[178:181], v[112:115]
	v_mfma_f32_16x16x32_bf16 v[100:103], v[222:225], v[186:189], v[100:103]
	v_mfma_f32_16x16x32_bf16 v[96:99], v[230:233], v[186:189], v[96:99]
	v_mfma_f32_16x16x32_bf16 v[84:87], v[222:225], v[206:209], v[84:87]
	v_mfma_f32_16x16x32_bf16 v[80:83], v[230:233], v[206:209], v[80:83]
	v_mfma_f32_16x16x32_bf16 v[68:71], v[222:225], v[214:217], v[68:71]
	v_mfma_f32_16x16x32_bf16 v[64:67], v[230:233], v[214:217], v[64:67]
	s_mov_b32 m0, s53
	s_barrier
	ds_read_b128 v[174:177], v168 offset:49152
	ds_read_b128 v[178:181], v168 offset:50176
	ds_read_b128 v[182:185], v168 offset:51200
	ds_read_b128 v[186:189], v168 offset:52224
	ds_read_b128 v[190:193], v168 offset:53248
	ds_read_b128 v[206:209], v168 offset:54272
	ds_read_b128 v[210:213], v168 offset:55296
	ds_read_b128 v[214:217], v168 offset:56320
	global_load_lds_dwordx4 v128, s[98:99]
	s_mov_b32 m0, s54
	s_nop 0
	global_load_lds_dwordx4 v132, s[98:99]
	s_barrier
	s_waitcnt lgkmcnt(0)
	v_mfma_f32_16x16x32_bf16 v[60:63], v[140:143], v[174:177], v[60:63]
	v_mfma_f32_16x16x32_bf16 v[56:59], v[148:151], v[174:177], v[56:59]
	v_mfma_f32_16x16x32_bf16 v[48:51], v[140:143], v[182:185], v[48:51]
	v_mfma_f32_16x16x32_bf16 v[40:43], v[148:151], v[182:185], v[40:43]
	v_mfma_f32_16x16x32_bf16 v[32:35], v[140:143], v[190:193], v[32:35]
	v_mfma_f32_16x16x32_bf16 v[24:27], v[148:151], v[190:193], v[24:27]
	v_mfma_f32_16x16x32_bf16 v[16:19], v[140:143], v[210:213], v[16:19]
	v_mfma_f32_16x16x32_bf16 v[8:11], v[148:151], v[210:213], v[8:11]
	v_mfma_f32_16x16x32_bf16 v[60:63], v[144:147], v[178:181], v[60:63]
	v_mfma_f32_16x16x32_bf16 v[56:59], v[170:173], v[178:181], v[56:59]
	v_mfma_f32_16x16x32_bf16 v[48:51], v[144:147], v[186:189], v[48:51]
	v_mfma_f32_16x16x32_bf16 v[40:43], v[170:173], v[186:189], v[40:43]
	v_mfma_f32_16x16x32_bf16 v[32:35], v[144:147], v[206:209], v[32:35]
	v_mfma_f32_16x16x32_bf16 v[24:27], v[170:173], v[206:209], v[24:27]
	v_mfma_f32_16x16x32_bf16 v[16:19], v[144:147], v[214:217], v[16:19]
	v_mfma_f32_16x16x32_bf16 v[8:11], v[170:173], v[214:217], v[8:11]
	s_barrier
	s_add_u32 s22, s22, 0x80080
	s_addc_u32 s23, s23, 0
	s_add_i32 s42, s42, s48
	s_mov_b32 m0, s42
	s_nop 0
	global_load_lds_dwordx4 v130, s[22:23]
	s_add_i32 m0, s42, 0x2000
	s_nop 0
	global_load_lds_dwordx4 v134, s[22:23]
	s_waitcnt vmcnt(6)
	s_barrier
	v_mfma_f32_16x16x32_bf16 v[52:55], v[218:221], v[174:177], v[52:55]
	v_mfma_f32_16x16x32_bf16 v[44:47], v[226:229], v[174:177], v[44:47]
	v_mfma_f32_16x16x32_bf16 v[36:39], v[218:221], v[182:185], v[36:39]
	v_mfma_f32_16x16x32_bf16 v[28:31], v[226:229], v[182:185], v[28:31]
	v_mfma_f32_16x16x32_bf16 v[20:23], v[218:221], v[190:193], v[20:23]
	v_mfma_f32_16x16x32_bf16 v[12:15], v[226:229], v[190:193], v[12:15]
	v_mfma_f32_16x16x32_bf16 v[4:7], v[218:221], v[210:213], v[4:7]
	v_mfma_f32_16x16x32_bf16 v[0:3], v[226:229], v[210:213], v[0:3]
	v_mfma_f32_16x16x32_bf16 v[52:55], v[222:225], v[178:181], v[52:55]
	v_mfma_f32_16x16x32_bf16 v[44:47], v[230:233], v[178:181], v[44:47]
	v_mfma_f32_16x16x32_bf16 v[36:39], v[222:225], v[186:189], v[36:39]
	v_mfma_f32_16x16x32_bf16 v[28:31], v[230:233], v[186:189], v[28:31]
	v_mfma_f32_16x16x32_bf16 v[20:23], v[222:225], v[206:209], v[20:23]
	v_mfma_f32_16x16x32_bf16 v[12:15], v[230:233], v[206:209], v[12:15]
	v_mfma_f32_16x16x32_bf16 v[4:7], v[222:225], v[214:217], v[4:7]
	v_mfma_f32_16x16x32_bf16 v[0:3], v[230:233], v[214:217], v[0:3]
	s_add_i32 s58, s58, 2
	s_add_u32 s20, s20, 0x100
	s_addc_u32 s21, s21, 0
	s_add_u32 s35, s35, 0x100
	s_addc_u32 s57, s57, 0
	s_cmp_gt_u32 s58, 29
	s_barrier
	s_cbranch_scc0 .LBB0_227
	v_lshl_add_u32 v140, s4, 8, v164
	s_cmp_gt_i32 s56, 23
	s_mov_b64 s[20:21], -1
	s_cbranch_scc1 .LBB0_262
	s_cmp_lt_i32 s56, 4
	s_cselect_b64 s[4:5], -1, 0
	s_and_b32 s6, s56, 0x7ffffffc
	s_cmp_eq_u32 s6, 16
	s_cselect_b64 s[6:7], -1, 0
	s_or_b64 s[20:21], s[4:5], s[6:7]
	s_and_b64 vcc, exec, s[20:21]
	v_mov_b32_e32 v149, v123
	v_mov_b32_e32 v148, v122
	v_mov_b32_e32 v163, v121
	v_mov_b32_e32 v162, v120
	v_mov_b32_e32 v147, v127
	v_mov_b32_e32 v146, v126
	v_mov_b32_e32 v151, v125
	v_mov_b32_e32 v150, v124
	s_cbranch_vccz .LBB0_231
	v_mul_f32_e32 v141, 0xbfb8aa3b, v124
	v_exp_f32_e32 v141, v141
	v_mul_f32_e32 v142, 0xbfb8aa3b, v120
	v_mul_f32_e32 v145, 0xbfb8aa3b, v126
	v_mul_f32_e32 v143, 0xbfb8aa3b, v125
	v_exp_f32_e32 v144, v142
	v_exp_f32_e32 v145, v145
	v_mul_f32_e32 v146, 0xbfb8aa3b, v122
	v_exp_f32_e32 v143, v143
	v_exp_f32_e32 v147, v146
	v_add_f32_e32 v141, 1.0, v141
	v_rcp_f32_e32 v142, v141
	v_add_f32_e32 v141, 1.0, v144
	v_add_f32_e32 v145, 1.0, v145
	v_rcp_f32_e32 v144, v141
	v_add_f32_e32 v141, 1.0, v143
	v_rcp_f32_e32 v146, v145
	v_add_f32_e32 v145, 1.0, v147
	v_mul_f32_e32 v147, 0xbfb8aa3b, v127
	v_rcp_f32_e32 v143, v141
	v_mul_f32_e32 v141, 0xbfb8aa3b, v121
	v_exp_f32_e32 v147, v147
	v_mul_f32_e32 v148, 0xbfb8aa3b, v123
	v_exp_f32_e32 v141, v141
	v_exp_f32_e32 v149, v148
	v_rcp_f32_e32 v148, v145
	v_add_f32_e32 v145, 1.0, v147
	v_add_f32_e32 v141, 1.0, v141
	v_rcp_f32_e32 v147, v145
	v_add_f32_e32 v145, 1.0, v149
	v_rcp_f32_e32 v149, v145
	v_rcp_f32_e32 v145, v141
	v_pk_mul_f32 v[146:147], v[126:127], v[146:147]
	v_pk_mul_f32 v[150:151], v[124:125], v[142:143]
	v_pk_mul_f32 v[148:149], v[122:123], v[148:149]
	v_pk_mul_f32 v[162:163], v[120:121], v[144:145]

.LBB0_561:
	s_add_u32 s38, s22, 0xfff80080
	s_addc_u32 s39, s23, -1
	s_add_i32 s84, 0, 0x10000
	ds_read_b128 v[72:75], v246
	ds_read_b128 v[76:79], v246 offset:1024
	ds_read_b128 v[84:87], v246 offset:2048
	ds_read_b128 v[92:95], v246 offset:3072
	s_cmp_eq_u32 s30, 28
	s_cselect_b32 s53, s5, s39
	s_cselect_b32 s52, s6, s38
	s_cselect_b32 s39, s1, s21
	s_cselect_b32 s38, s7, s17
	s_add_i32 m0, s61, 0xc000
	ds_read_b128 v[144:147], v208
	ds_read_b128 v[148:151], v208 offset:1024
	ds_read_b128 v[188:191], v208 offset:2048
	ds_read_b128 v[210:213], v208 offset:3072
	ds_read_b128 v[214:217], v208 offset:4096
	ds_read_b128 v[218:221], v208 offset:5120
	ds_read_b128 v[222:225], v208 offset:6144
	ds_read_b128 v[226:229], v208 offset:7168
	global_load_lds_dwordx4 v184, s[22:23]
	s_add_i32 m0, s61, 0xe000
	s_nop 0
	global_load_lds_dwordx4 v186, s[22:23]
	s_waitcnt lgkmcnt(8)
	s_barrier
	s_waitcnt lgkmcnt(0)
	v_mfma_f32_16x16x32_bf16 v[140:143], v[72:75], v[144:147], v[140:143]
	v_mfma_f32_16x16x32_bf16 v[136:139], v[84:87], v[144:147], v[136:139]
	v_mfma_f32_16x16x32_bf16 v[124:127], v[72:75], v[188:191], v[124:127]
	v_mfma_f32_16x16x32_bf16 v[120:123], v[84:87], v[188:191], v[120:123]
	v_mfma_f32_16x16x32_bf16 v[108:111], v[72:75], v[214:217], v[108:111]
	v_mfma_f32_16x16x32_bf16 v[104:107], v[84:87], v[214:217], v[104:107]
	v_mfma_f32_16x16x32_bf16 v[88:91], v[72:75], v[222:225], v[88:91]
	v_mfma_f32_16x16x32_bf16 v[80:83], v[84:87], v[222:225], v[80:83]
	v_mfma_f32_16x16x32_bf16 v[140:143], v[76:79], v[148:151], v[140:143]
	v_mfma_f32_16x16x32_bf16 v[136:139], v[92:95], v[148:151], v[136:139]
	v_mfma_f32_16x16x32_bf16 v[124:127], v[76:79], v[210:213], v[124:127]
	v_mfma_f32_16x16x32_bf16 v[120:123], v[92:95], v[210:213], v[120:123]
	v_mfma_f32_16x16x32_bf16 v[108:111], v[76:79], v[218:221], v[108:111]
	v_mfma_f32_16x16x32_bf16 v[104:107], v[92:95], v[218:221], v[104:107]
	v_mfma_f32_16x16x32_bf16 v[88:91], v[76:79], v[226:229], v[88:91]
	v_mfma_f32_16x16x32_bf16 v[80:83], v[92:95], v[226:229], v[80:83]
	s_barrier
	s_add_i32 s86, 0, 0x14000
	s_add_i32 s84, s84, s60
	ds_read_b128 v[230:233], v247
	ds_read_b128 v[234:237], v247 offset:1024
	ds_read_b128 v[238:241], v247 offset:2048
	ds_read_b128 v[242:245], v247 offset:3072
	s_mov_b32 m0, s84
	s_nop 0
	global_load_lds_dwordx4 v152, s[38:39]
	s_add_i32 m0, s84, 0x2000
	s_nop 0
	global_load_lds_dwordx4 v162, s[38:39]
	s_barrier
	s_waitcnt lgkmcnt(0)
	v_mfma_f32_16x16x32_bf16 v[132:135], v[230:233], v[144:147], v[132:135]
	v_mfma_f32_16x16x32_bf16 v[128:131], v[238:241], v[144:147], v[128:131]
	v_mfma_f32_16x16x32_bf16 v[116:119], v[230:233], v[188:191], v[116:119]
	v_mfma_f32_16x16x32_bf16 v[112:115], v[238:241], v[188:191], v[112:115]
	v_mfma_f32_16x16x32_bf16 v[100:103], v[230:233], v[214:217], v[100:103]
	v_mfma_f32_16x16x32_bf16 v[96:99], v[238:241], v[214:217], v[96:99]
	v_mfma_f32_16x16x32_bf16 v[68:71], v[230:233], v[222:225], v[68:71]
	v_mfma_f32_16x16x32_bf16 v[64:67], v[238:241], v[222:225], v[64:67]
	v_mfma_f32_16x16x32_bf16 v[132:135], v[234:237], v[148:151], v[132:135]
	v_mfma_f32_16x16x32_bf16 v[128:131], v[242:245], v[148:151], v[128:131]
	v_mfma_f32_16x16x32_bf16 v[116:119], v[234:237], v[210:213], v[116:119]
	v_mfma_f32_16x16x32_bf16 v[112:115], v[242:245], v[210:213], v[112:115]
	v_mfma_f32_16x16x32_bf16 v[100:103], v[234:237], v[218:221], v[100:103]
	v_mfma_f32_16x16x32_bf16 v[96:99], v[242:245], v[218:221], v[96:99]
	v_mfma_f32_16x16x32_bf16 v[68:71], v[234:237], v[226:229], v[68:71]
	v_mfma_f32_16x16x32_bf16 v[64:67], v[242:245], v[226:229], v[64:67]
	s_mov_b32 m0, s61
	s_add_u32 s98, s52, 0x80
	s_addc_u32 s99, s53, 0
	s_barrier
	ds_read_b128 v[144:147], v208 offset:16384
	ds_read_b128 v[148:151], v208 offset:17408
	ds_read_b128 v[188:191], v208 offset:18432
	ds_read_b128 v[210:213], v208 offset:19456
	ds_read_b128 v[214:217], v208 offset:20480
	ds_read_b128 v[218:221], v208 offset:21504
	ds_read_b128 v[222:225], v208 offset:22528
	ds_read_b128 v[226:229], v208 offset:23552
	global_load_lds_dwordx4 v166, s[52:53]
	s_mov_b32 m0, s62
	s_nop 0
	global_load_lds_dwordx4 v164, s[52:53]
	s_barrier
	s_waitcnt lgkmcnt(0)
	v_mfma_f32_16x16x32_bf16 v[60:63], v[72:75], v[144:147], v[60:63]
	v_mfma_f32_16x16x32_bf16 v[56:59], v[84:87], v[144:147], v[56:59]
	v_mfma_f32_16x16x32_bf16 v[44:47], v[72:75], v[188:191], v[44:47]
	v_mfma_f32_16x16x32_bf16 v[40:43], v[84:87], v[188:191], v[40:43]
	v_mfma_f32_16x16x32_bf16 v[28:31], v[72:75], v[214:217], v[28:31]
	v_mfma_f32_16x16x32_bf16 v[24:27], v[84:87], v[214:217], v[24:27]
	v_mfma_f32_16x16x32_bf16 v[12:15], v[72:75], v[222:225], v[12:15]
	v_mfma_f32_16x16x32_bf16 v[8:11], v[84:87], v[222:225], v[8:11]
	v_mfma_f32_16x16x32_bf16 v[60:63], v[76:79], v[148:151], v[60:63]
	v_mfma_f32_16x16x32_bf16 v[56:59], v[92:95], v[148:151], v[56:59]
	v_mfma_f32_16x16x32_bf16 v[44:47], v[76:79], v[210:213], v[44:47]
	v_mfma_f32_16x16x32_bf16 v[40:43], v[92:95], v[210:213], v[40:43]
	v_mfma_f32_16x16x32_bf16 v[28:31], v[76:79], v[218:221], v[28:31]
	v_mfma_f32_16x16x32_bf16 v[24:27], v[92:95], v[218:221], v[24:27]
	v_mfma_f32_16x16x32_bf16 v[12:15], v[76:79], v[226:229], v[12:15]
	v_mfma_f32_16x16x32_bf16 v[8:11], v[92:95], v[226:229], v[8:11]
	s_barrier
	s_add_u32 s84, s38, 0x80000
	s_addc_u32 s85, s39, 0
	s_add_i32 s86, s86, s60
	s_mov_b32 m0, s86
	s_nop 0
	global_load_lds_dwordx4 v152, s[84:85]
	s_add_i32 m0, s86, 0x2000
	s_nop 0
	global_load_lds_dwordx4 v162, s[84:85]
	s_waitcnt vmcnt(6)
	s_barrier
	v_mfma_f32_16x16x32_bf16 v[52:55], v[230:233], v[144:147], v[52:55]
	v_mfma_f32_16x16x32_bf16 v[48:51], v[238:241], v[144:147], v[48:51]
	v_mfma_f32_16x16x32_bf16 v[36:39], v[230:233], v[188:191], v[36:39]
	v_mfma_f32_16x16x32_bf16 v[32:35], v[238:241], v[188:191], v[32:35]
	v_mfma_f32_16x16x32_bf16 v[20:23], v[230:233], v[214:217], v[20:23]
	v_mfma_f32_16x16x32_bf16 v[16:19], v[238:241], v[214:217], v[16:19]
	v_mfma_f32_16x16x32_bf16 v[4:7], v[230:233], v[222:225], v[4:7]
	v_mfma_f32_16x16x32_bf16 v[0:3], v[238:241], v[222:225], v[0:3]
	v_mfma_f32_16x16x32_bf16 v[52:55], v[234:237], v[148:151], v[52:55]
	v_mfma_f32_16x16x32_bf16 v[48:51], v[242:245], v[148:151], v[48:51]
	v_mfma_f32_16x16x32_bf16 v[36:39], v[234:237], v[210:213], v[36:39]
	v_mfma_f32_16x16x32_bf16 v[32:35], v[242:245], v[210:213], v[32:35]
	v_mfma_f32_16x16x32_bf16 v[20:23], v[234:237], v[218:221], v[20:23]
	v_mfma_f32_16x16x32_bf16 v[16:19], v[242:245], v[218:221], v[16:19]
	v_mfma_f32_16x16x32_bf16 v[4:7], v[234:237], v[226:229], v[4:7]
	v_mfma_f32_16x16x32_bf16 v[0:3], v[242:245], v[226:229], v[0:3]
	s_add_i32 s84, 0, 0x18000
	s_barrier
	ds_read_b128 v[72:75], v248
	ds_read_b128 v[76:79], v248 offset:1024
	ds_read_b128 v[84:87], v248 offset:2048
	ds_read_b128 v[92:95], v248 offset:3072
	s_add_u32 s52, s52, 0x80000
	s_addc_u32 s53, s53, 0
	s_mov_b32 m0, s63
	ds_read_b128 v[144:147], v208 offset:32768
	ds_read_b128 v[148:151], v208 offset:33792
	ds_read_b128 v[188:191], v208 offset:34816
	ds_read_b128 v[210:213], v208 offset:35840
	ds_read_b128 v[214:217], v208 offset:36864
	ds_read_b128 v[218:221], v208 offset:37888
	ds_read_b128 v[222:225], v208 offset:38912
	ds_read_b128 v[226:229], v208 offset:39936
	global_load_lds_dwordx4 v166, s[52:53]
	s_mov_b32 m0, s68
	s_nop 0
	global_load_lds_dwordx4 v164, s[52:53]
	s_waitcnt lgkmcnt(8)
	s_barrier
	s_waitcnt lgkmcnt(0)
	v_mfma_f32_16x16x32_bf16 v[140:143], v[72:75], v[144:147], v[140:143]
	v_mfma_f32_16x16x32_bf16 v[136:139], v[84:87], v[144:147], v[136:139]
	v_mfma_f32_16x16x32_bf16 v[124:127], v[72:75], v[188:191], v[124:127]
	v_mfma_f32_16x16x32_bf16 v[120:123], v[84:87], v[188:191], v[120:123]
	v_mfma_f32_16x16x32_bf16 v[108:111], v[72:75], v[214:217], v[108:111]
	v_mfma_f32_16x16x32_bf16 v[104:107], v[84:87], v[214:217], v[104:107]
	v_mfma_f32_16x16x32_bf16 v[88:91], v[72:75], v[222:225], v[88:91]
	v_mfma_f32_16x16x32_bf16 v[80:83], v[84:87], v[222:225], v[80:83]
	v_mfma_f32_16x16x32_bf16 v[140:143], v[76:79], v[148:151], v[140:143]
	v_mfma_f32_16x16x32_bf16 v[136:139], v[92:95], v[148:151], v[136:139]
	v_mfma_f32_16x16x32_bf16 v[124:127], v[76:79], v[210:213], v[124:127]
	v_mfma_f32_16x16x32_bf16 v[120:123], v[92:95], v[210:213], v[120:123]
	v_mfma_f32_16x16x32_bf16 v[108:111], v[76:79], v[218:221], v[108:111]
	v_mfma_f32_16x16x32_bf16 v[104:107], v[92:95], v[218:221], v[104:107]
	v_mfma_f32_16x16x32_bf16 v[88:91], v[76:79], v[226:229], v[88:91]
	v_mfma_f32_16x16x32_bf16 v[80:83], v[92:95], v[226:229], v[80:83]
	s_barrier
	s_add_i32 s52, 0, 0x1c000
	s_add_i32 s53, s84, s60
	s_add_u32 s100, s38, 0x80
	s_addc_u32 s101, s39, 0
	s_mov_b32 m0, s53
	ds_read_b128 v[230:233], v249
	ds_read_b128 v[234:237], v249 offset:1024
	ds_read_b128 v[238:241], v249 offset:2048
	ds_read_b128 v[242:245], v249 offset:3072
	global_load_lds_dwordx4 v152, s[100:101]
	s_add_i32 m0, s53, 0x2000
	s_nop 0
	global_load_lds_dwordx4 v162, s[100:101]
	s_barrier
	s_waitcnt lgkmcnt(0)
	v_mfma_f32_16x16x32_bf16 v[132:135], v[230:233], v[144:147], v[132:135]
	v_mfma_f32_16x16x32_bf16 v[128:131], v[238:241], v[144:147], v[128:131]
	v_mfma_f32_16x16x32_bf16 v[116:119], v[230:233], v[188:191], v[116:119]
	v_mfma_f32_16x16x32_bf16 v[112:115], v[238:241], v[188:191], v[112:115]
	v_mfma_f32_16x16x32_bf16 v[100:103], v[230:233], v[214:217], v[100:103]
	v_mfma_f32_16x16x32_bf16 v[96:99], v[238:241], v[214:217], v[96:99]
	v_mfma_f32_16x16x32_bf16 v[68:71], v[230:233], v[222:225], v[68:71]
	v_mfma_f32_16x16x32_bf16 v[64:67], v[238:241], v[222:225], v[64:67]
	v_mfma_f32_16x16x32_bf16 v[132:135], v[234:237], v[148:151], v[132:135]
	v_mfma_f32_16x16x32_bf16 v[128:131], v[242:245], v[148:151], v[128:131]
	v_mfma_f32_16x16x32_bf16 v[116:119], v[234:237], v[210:213], v[116:119]
	v_mfma_f32_16x16x32_bf16 v[112:115], v[242:245], v[210:213], v[112:115]
	v_mfma_f32_16x16x32_bf16 v[100:103], v[234:237], v[218:221], v[100:103]
	v_mfma_f32_16x16x32_bf16 v[96:99], v[242:245], v[218:221], v[96:99]
	v_mfma_f32_16x16x32_bf16 v[68:71], v[234:237], v[226:229], v[68:71]
	v_mfma_f32_16x16x32_bf16 v[64:67], v[242:245], v[226:229], v[64:67]
	s_mov_b32 m0, s81
	s_barrier
	ds_read_b128 v[144:147], v208 offset:49152
	ds_read_b128 v[148:151], v208 offset:50176
	ds_read_b128 v[188:191], v208 offset:51200
	ds_read_b128 v[210:213], v208 offset:52224
	ds_read_b128 v[214:217], v208 offset:53248
	ds_read_b128 v[218:221], v208 offset:54272
	ds_read_b128 v[222:225], v208 offset:55296
	ds_read_b128 v[226:229], v208 offset:56320
	global_load_lds_dwordx4 v166, s[98:99]
	s_mov_b32 m0, s82
	s_nop 0
	global_load_lds_dwordx4 v164, s[98:99]
	s_barrier
	s_waitcnt lgkmcnt(0)
	v_mfma_f32_16x16x32_bf16 v[60:63], v[72:75], v[144:147], v[60:63]
	v_mfma_f32_16x16x32_bf16 v[56:59], v[84:87], v[144:147], v[56:59]
	v_mfma_f32_16x16x32_bf16 v[44:47], v[72:75], v[188:191], v[44:47]
	v_mfma_f32_16x16x32_bf16 v[40:43], v[84:87], v[188:191], v[40:43]
	v_mfma_f32_16x16x32_bf16 v[28:31], v[72:75], v[214:217], v[28:31]
	v_mfma_f32_16x16x32_bf16 v[24:27], v[84:87], v[214:217], v[24:27]
	v_mfma_f32_16x16x32_bf16 v[12:15], v[72:75], v[222:225], v[12:15]
	v_mfma_f32_16x16x32_bf16 v[8:11], v[84:87], v[222:225], v[8:11]
	v_mfma_f32_16x16x32_bf16 v[60:63], v[76:79], v[148:151], v[60:63]
	v_mfma_f32_16x16x32_bf16 v[56:59], v[92:95], v[148:151], v[56:59]
	v_mfma_f32_16x16x32_bf16 v[44:47], v[76:79], v[210:213], v[44:47]
	v_mfma_f32_16x16x32_bf16 v[40:43], v[92:95], v[210:213], v[40:43]
	v_mfma_f32_16x16x32_bf16 v[28:31], v[76:79], v[218:221], v[28:31]
	v_mfma_f32_16x16x32_bf16 v[24:27], v[92:95], v[218:221], v[24:27]
	v_mfma_f32_16x16x32_bf16 v[12:15], v[76:79], v[226:229], v[12:15]
	v_mfma_f32_16x16x32_bf16 v[8:11], v[92:95], v[226:229], v[8:11]
	s_barrier
	s_add_u32 s38, s38, 0x80080
	s_addc_u32 s39, s39, 0
	s_add_i32 s52, s52, s60
	s_mov_b32 m0, s52
	s_nop 0
	global_load_lds_dwordx4 v152, s[38:39]
	s_add_i32 m0, s52, 0x2000
	s_nop 0
	global_load_lds_dwordx4 v162, s[38:39]
	s_waitcnt vmcnt(6)
	s_barrier
	v_mfma_f32_16x16x32_bf16 v[52:55], v[230:233], v[144:147], v[52:55]
	v_mfma_f32_16x16x32_bf16 v[48:51], v[238:241], v[144:147], v[48:51]
	v_mfma_f32_16x16x32_bf16 v[36:39], v[230:233], v[188:191], v[36:39]
	v_mfma_f32_16x16x32_bf16 v[32:35], v[238:241], v[188:191], v[32:35]
	v_mfma_f32_16x16x32_bf16 v[20:23], v[230:233], v[214:217], v[20:23]
	v_mfma_f32_16x16x32_bf16 v[16:19], v[238:241], v[214:217], v[16:19]
	v_mfma_f32_16x16x32_bf16 v[4:7], v[230:233], v[222:225], v[4:7]
	v_mfma_f32_16x16x32_bf16 v[0:3], v[238:241], v[222:225], v[0:3]
	v_mfma_f32_16x16x32_bf16 v[52:55], v[234:237], v[148:151], v[52:55]
	v_mfma_f32_16x16x32_bf16 v[48:51], v[242:245], v[148:151], v[48:51]
	v_mfma_f32_16x16x32_bf16 v[36:39], v[234:237], v[210:213], v[36:39]
	v_mfma_f32_16x16x32_bf16 v[32:35], v[242:245], v[210:213], v[32:35]
	v_mfma_f32_16x16x32_bf16 v[20:23], v[234:237], v[218:221], v[20:23]
	v_mfma_f32_16x16x32_bf16 v[16:19], v[242:245], v[218:221], v[16:19]
	v_mfma_f32_16x16x32_bf16 v[4:7], v[234:237], v[226:229], v[4:7]
	v_mfma_f32_16x16x32_bf16 v[0:3], v[242:245], v[226:229], v[0:3]
	s_add_i32 s30, s30, 2
	s_add_u32 s22, s22, 0x100
	s_addc_u32 s23, s23, 0
	s_add_u32 s17, s17, 0x100
	s_addc_u32 s21, s21, 0
	s_cmp_gt_u32 s30, 29
	s_barrier
	s_cbranch_scc0 .LBB0_561
	v_lshl_or_b32 v188, s4, 8, v207
	v_ashrrev_i32_e32 v189, 31, v188
	s_cmp_lt_i32 s20, 16
	s_cselect_b32 s6, s44, s46
	s_cselect_b32 s7, s45, s47
	s_cselect_b32 s1, 0, 16
	s_sub_i32 s4, s20, s1
	s_mov_b32 s5, 0
	s_lshl_b64 s[4:5], s[4:5], 21
	s_add_u32 s38, s6, s4
	s_addc_u32 s39, s7, s5
	s_cmp_lt_i32 s20, 32
	s_cselect_b32 s1, 0x3000, s73
	s_cmp_lt_i32 s20, 16
	s_cselect_b32 s1, 0, s1
	s_lshl_b32 s1, s1, 2
	s_add_u32 s6, s79, s1
	s_addc_u32 s7, s80, 0
	s_mov_b32 s4, s20
	s_mov_b32 s5, 0
	s_lshl_b64 s[4:5], s[4:5], 20
	s_add_u32 s52, s69, s4
	s_addc_u32 s53, s78, s5
	v_lshl_add_u64 v[190:191], v[188:189], 2, s[6:7]
	s_mov_b64 s[4:5], 0x28504000
	v_lshl_add_u64 v[190:191], v[190:191], 0, s[4:5]
	global_load_dwordx4 v[92:95], v[190:191], off
	global_load_dwordx4 v[84:87], v[190:191], off offset:16
	global_load_dwordx4 v[76:79], v[190:191], off offset:512
	global_load_dwordx4 v[72:75], v[190:191], off offset:528
	v_lshl_add_u64 v[144:145], v[188:189], 1, s[52:53]
	s_and_b64 vcc, exec, s[64:65]
	s_cbranch_vccz .Lwo_epi_f32
	v_lshl_add_u64 v[148:149], v[168:169], 1, v[144:145]
	global_load_dwordx4 v[210:213], v[148:149], off
	global_load_dwordx4 v[214:217], v[148:149], off offset:256
	v_lshl_add_u64 v[148:149], v[170:171], 1, v[144:145]
	global_load_dwordx4 v[218:221], v[148:149], off
	global_load_dwordx4 v[222:225], v[148:149], off offset:256
	v_lshl_add_u64 v[148:149], v[172:173], 1, v[144:145]
	global_load_dwordx4 v[226:229], v[148:149], off
	global_load_dwordx4 v[230:233], v[148:149], off offset:256
	v_lshl_add_u64 v[148:149], v[174:175], 1, v[144:145]
	global_load_dwordx4 v[234:237], v[148:149], off
	global_load_dwordx4 v[238:241], v[148:149], off offset:256
	v_lshl_add_u64 v[148:149], v[176:177], 1, v[144:145]
	global_load_dwordx4 v[242:245], v[148:149], off
	s_waitcnt vmcnt(8)
	v_lshlrev_b32_e32 v188, 16, v210
	v_and_b32_e32 v189, 0xffff0000, v210
	v_lshlrev_b32_e32 v190, 16, v211
	v_and_b32_e32 v191, 0xffff0000, v211
	v_lshlrev_b32_e32 v246, 16, v212
	v_and_b32_e32 v247, 0xffff0000, v212
	v_lshlrev_b32_e32 v248, 16, v213
	v_and_b32_e32 v249, 0xffff0000, v213
	global_load_dwordx4 v[210:213], v[148:149], off offset:256
	v_lshl_add_u64 v[150:151], v[168:169], 1, v[144:145]
	v_pk_fma_f32 v[140:141], v[140:141], v[92:93], v[188:189]
	v_pk_fma_f32 v[142:143], v[142:143], v[94:95], v[190:191]
	v_pk_fma_f32 v[136:137], v[136:137], v[84:85], v[246:247]
	v_pk_fma_f32 v[138:139], v[138:139], v[86:87], v[248:249]
	v_cvt_pk_bf16_f32 v140, v140, v141
	v_cvt_pk_bf16_f32 v141, v142, v143
	v_cvt_pk_bf16_f32 v142, v136, v137
	v_cvt_pk_bf16_f32 v143, v138, v139
	global_store_dwordx4 v[150:151], v[140:143], off
	s_waitcnt vmcnt(9)
	v_lshlrev_b32_e32 v188, 16, v214
	v_and_b32_e32 v189, 0xffff0000, v214
	v_lshlrev_b32_e32 v190, 16, v215
	v_and_b32_e32 v191, 0xffff0000, v215
	v_lshlrev_b32_e32 v246, 16, v216
	v_and_b32_e32 v247, 0xffff0000, v216
	v_lshlrev_b32_e32 v248, 16, v217
	v_and_b32_e32 v249, 0xffff0000, v217
	v_lshl_add_u64 v[148:149], v[178:179], 1, v[144:145]
	global_load_dwordx4 v[214:217], v[148:149], off
	v_pk_fma_f32 v[132:133], v[132:133], v[76:77], v[188:189]
	v_pk_fma_f32 v[134:135], v[134:135], v[78:79], v[190:191]
	v_pk_fma_f32 v[128:129], v[128:129], v[72:73], v[246:247]
	v_pk_fma_f32 v[130:131], v[130:131], v[74:75], v[248:249]
	v_cvt_pk_bf16_f32 v132, v132, v133
	v_cvt_pk_bf16_f32 v133, v134, v135
	v_cvt_pk_bf16_f32 v134, v128, v129
	v_cvt_pk_bf16_f32 v135, v130, v131
	global_store_dwordx4 v[150:151], v[132:135], off offset:256
	s_waitcnt vmcnt(10)
	v_lshlrev_b32_e32 v188, 16, v218
	v_and_b32_e32 v189, 0xffff0000, v218
	v_lshlrev_b32_e32 v190, 16, v219
	v_and_b32_e32 v191, 0xffff0000, v219
	v_lshlrev_b32_e32 v246, 16, v220
	v_and_b32_e32 v247, 0xffff0000, v220
	v_lshlrev_b32_e32 v248, 16, v221
	v_and_b32_e32 v249, 0xffff0000, v221
	global_load_dwordx4 v[218:221], v[148:149], off offset:256
	v_lshl_add_u64 v[192:193], v[170:171], 1, v[144:145]
	v_pk_fma_f32 v[124:125], v[124:125], v[92:93], v[188:189]
	v_pk_fma_f32 v[126:127], v[126:127], v[94:95], v[190:191]
	v_pk_fma_f32 v[120:121], v[120:121], v[84:85], v[246:247]
	v_pk_fma_f32 v[122:123], v[122:123], v[86:87], v[248:249]
	v_cvt_pk_bf16_f32 v124, v124, v125
	v_cvt_pk_bf16_f32 v125, v126, v127
	v_cvt_pk_bf16_f32 v126, v120, v121
	v_cvt_pk_bf16_f32 v127, v122, v123
	global_store_dwordx4 v[192:193], v[124:127], off
	s_waitcnt vmcnt(11)
	v_lshlrev_b32_e32 v188, 16, v222
	v_and_b32_e32 v189, 0xffff0000, v222
	v_lshlrev_b32_e32 v190, 16, v223
	v_and_b32_e32 v191, 0xffff0000, v223
	v_lshlrev_b32_e32 v246, 16, v224
	v_and_b32_e32 v247, 0xffff0000, v224
	v_lshlrev_b32_e32 v248, 16, v225
	v_and_b32_e32 v249, 0xffff0000, v225
	v_lshl_add_u64 v[148:149], v[180:181], 1, v[144:145]
	global_load_dwordx4 v[222:225], v[148:149], off
	v_pk_fma_f32 v[116:117], v[116:117], v[76:77], v[188:189]
	v_pk_fma_f32 v[118:119], v[118:119], v[78:79], v[190:191]
	v_pk_fma_f32 v[112:113], v[112:113], v[72:73], v[246:247]
	v_pk_fma_f32 v[114:115], v[114:115], v[74:75], v[248:249]
	v_cvt_pk_bf16_f32 v116, v116, v117
	v_cvt_pk_bf16_f32 v117, v118, v119
	v_cvt_pk_bf16_f32 v118, v112, v113
	v_cvt_pk_bf16_f32 v119, v114, v115
	global_store_dwordx4 v[192:193], v[116:119], off offset:256
	s_waitcnt vmcnt(12)
	v_lshlrev_b32_e32 v188, 16, v226
	v_and_b32_e32 v189, 0xffff0000, v226
	v_lshlrev_b32_e32 v190, 16, v227
	v_and_b32_e32 v191, 0xffff0000, v227
	v_lshlrev_b32_e32 v246, 16, v228
	v_and_b32_e32 v247, 0xffff0000, v228
	v_lshlrev_b32_e32 v248, 16, v229
	v_and_b32_e32 v249, 0xffff0000, v229
	global_load_dwordx4 v[226:229], v[148:149], off offset:256
	v_lshl_add_u64 v[150:151], v[172:173], 1, v[144:145]
	v_pk_fma_f32 v[108:109], v[108:109], v[92:93], v[188:189]
	v_pk_fma_f32 v[110:111], v[110:111], v[94:95], v[190:191]
	v_pk_fma_f32 v[104:105], v[104:105], v[84:85], v[246:247]
	v_pk_fma_f32 v[106:107], v[106:107], v[86:87], v[248:249]
	v_cvt_pk_bf16_f32 v108, v108, v109
	v_cvt_pk_bf16_f32 v109, v110, v111
	v_cvt_pk_bf16_f32 v110, v104, v105
	v_cvt_pk_bf16_f32 v111, v106, v107
	global_store_dwordx4 v[150:151], v[108:111], off
	s_waitcnt vmcnt(13)
	v_lshlrev_b32_e32 v188, 16, v230
	v_and_b32_e32 v189, 0xffff0000, v230
	v_lshlrev_b32_e32 v190, 16, v231
	v_and_b32_e32 v191, 0xffff0000, v231
	v_lshlrev_b32_e32 v246, 16, v232
	v_and_b32_e32 v247, 0xffff0000, v232
	v_lshlrev_b32_e32 v248, 16, v233
	v_and_b32_e32 v249, 0xffff0000, v233
	v_lshl_add_u64 v[148:149], v[182:183], 1, v[144:145]
	global_load_dwordx4 v[230:233], v[148:149], off
	v_pk_fma_f32 v[100:101], v[100:101], v[76:77], v[188:189]
	v_pk_fma_f32 v[102:103], v[102:103], v[78:79], v[190:191]
	v_pk_fma_f32 v[96:97], v[96:97], v[72:73], v[246:247]
	v_pk_fma_f32 v[98:99], v[98:99], v[74:75], v[248:249]
	v_cvt_pk_bf16_f32 v100, v100, v101
	v_cvt_pk_bf16_f32 v101, v102, v103
	v_cvt_pk_bf16_f32 v102, v96, v97
	v_cvt_pk_bf16_f32 v103, v98, v99
	global_store_dwordx4 v[150:151], v[100:103], off offset:256
	s_waitcnt vmcnt(14)
	v_lshlrev_b32_e32 v188, 16, v234
	v_and_b32_e32 v189, 0xffff0000, v234
	v_lshlrev_b32_e32 v190, 16, v235
	v_and_b32_e32 v191, 0xffff0000, v235
	v_lshlrev_b32_e32 v246, 16, v236
	v_and_b32_e32 v247, 0xffff0000, v236
	v_lshlrev_b32_e32 v248, 16, v237
	v_and_b32_e32 v249, 0xffff0000, v237
	global_load_dwordx4 v[234:237], v[148:149], off offset:256
	v_lshl_add_u64 v[192:193], v[174:175], 1, v[144:145]
	v_pk_fma_f32 v[88:89], v[88:89], v[92:93], v[188:189]
	v_pk_fma_f32 v[90:91], v[90:91], v[94:95], v[190:191]
	v_pk_fma_f32 v[80:81], v[80:81], v[84:85], v[246:247]
	v_pk_fma_f32 v[82:83], v[82:83], v[86:87], v[248:249]
	v_cvt_pk_bf16_f32 v88, v88, v89
	v_cvt_pk_bf16_f32 v89, v90, v91
	v_cvt_pk_bf16_f32 v90, v80, v81
	v_cvt_pk_bf16_f32 v91, v82, v83
	global_store_dwordx4 v[192:193], v[88:91], off
	s_waitcnt vmcnt(15)
	v_lshlrev_b32_e32 v188, 16, v238
	v_and_b32_e32 v189, 0xffff0000, v238
	v_lshlrev_b32_e32 v190, 16, v239
	v_and_b32_e32 v191, 0xffff0000, v239
	v_lshlrev_b32_e32 v246, 16, v240
	v_and_b32_e32 v247, 0xffff0000, v240
	v_lshlrev_b32_e32 v248, 16, v241
	v_and_b32_e32 v249, 0xffff0000, v241
	v_pk_fma_f32 v[68:69], v[68:69], v[76:77], v[188:189]
	v_pk_fma_f32 v[70:71], v[70:71], v[78:79], v[190:191]
	v_pk_fma_f32 v[64:65], v[64:65], v[72:73], v[246:247]
	v_pk_fma_f32 v[66:67], v[66:67], v[74:75], v[248:249]
	v_cvt_pk_bf16_f32 v68, v68, v69
	v_cvt_pk_bf16_f32 v69, v70, v71
	v_cvt_pk_bf16_f32 v70, v64, v65
	v_cvt_pk_bf16_f32 v71, v66, v67
	global_store_dwordx4 v[192:193], v[68:71], off offset:256
	s_waitcnt vmcnt(15)
	v_lshlrev_b32_e32 v188, 16, v242
	v_and_b32_e32 v189, 0xffff0000, v242
	v_lshlrev_b32_e32 v190, 16, v243
	v_and_b32_e32 v191, 0xffff0000, v243
	v_lshlrev_b32_e32 v246, 16, v244
	v_and_b32_e32 v247, 0xffff0000, v244
	v_lshlrev_b32_e32 v248, 16, v245
	v_and_b32_e32 v249, 0xffff0000, v245
	v_lshl_add_u64 v[150:151], v[176:177], 1, v[144:145]
	v_pk_fma_f32 v[60:61], v[60:61], v[92:93], v[188:189]
	v_pk_fma_f32 v[62:63], v[62:63], v[94:95], v[190:191]
	v_pk_fma_f32 v[56:57], v[56:57], v[84:85], v[246:247]
	v_pk_fma_f32 v[58:59], v[58:59], v[86:87], v[248:249]
	v_cvt_pk_bf16_f32 v60, v60, v61
	v_cvt_pk_bf16_f32 v61, v62, v63
	v_cvt_pk_bf16_f32 v62, v56, v57
	v_cvt_pk_bf16_f32 v63, v58, v59
	global_store_dwordx4 v[150:151], v[60:63], off
	s_waitcnt vmcnt(15)
	v_lshlrev_b32_e32 v188, 16, v210
	v_and_b32_e32 v189, 0xffff0000, v210
	v_lshlrev_b32_e32 v190, 16, v211
	v_and_b32_e32 v191, 0xffff0000, v211
	v_lshlrev_b32_e32 v246, 16, v212
	v_and_b32_e32 v247, 0xffff0000, v212
	v_lshlrev_b32_e32 v248, 16, v213
	v_and_b32_e32 v249, 0xffff0000, v213
	v_pk_fma_f32 v[52:53], v[52:53], v[76:77], v[188:189]
	v_pk_fma_f32 v[54:55], v[54:55], v[78:79], v[190:191]
	v_pk_fma_f32 v[48:49], v[48:49], v[72:73], v[246:247]
	v_pk_fma_f32 v[50:51], v[50:51], v[74:75], v[248:249]
	v_cvt_pk_bf16_f32 v52, v52, v53
	v_cvt_pk_bf16_f32 v53, v54, v55
	v_cvt_pk_bf16_f32 v54, v48, v49
	v_cvt_pk_bf16_f32 v55, v50, v51
	global_store_dwordx4 v[150:151], v[52:55], off offset:256
	s_waitcnt vmcnt(14)
	v_lshlrev_b32_e32 v188, 16, v214
	v_and_b32_e32 v189, 0xffff0000, v214
	v_lshlrev_b32_e32 v190, 16, v215
	v_and_b32_e32 v191, 0xffff0000, v215
	v_lshlrev_b32_e32 v246, 16, v216
	v_and_b32_e32 v247, 0xffff0000, v216
	v_lshlrev_b32_e32 v248, 16, v217
	v_and_b32_e32 v249, 0xffff0000, v217
	v_lshl_add_u64 v[192:193], v[178:179], 1, v[144:145]
	v_pk_fma_f32 v[44:45], v[44:45], v[92:93], v[188:189]
	v_pk_fma_f32 v[46:47], v[46:47], v[94:95], v[190:191]
	v_pk_fma_f32 v[40:41], v[40:41], v[84:85], v[246:247]
	v_pk_fma_f32 v[42:43], v[42:43], v[86:87], v[248:249]
	v_cvt_pk_bf16_f32 v44, v44, v45
	v_cvt_pk_bf16_f32 v45, v46, v47
	v_cvt_pk_bf16_f32 v46, v40, v41
	v_cvt_pk_bf16_f32 v47, v42, v43
	global_store_dwordx4 v[192:193], v[44:47], off
	s_waitcnt vmcnt(13)
	v_lshlrev_b32_e32 v188, 16, v218
	v_and_b32_e32 v189, 0xffff0000, v218
	v_lshlrev_b32_e32 v190, 16, v219
	v_and_b32_e32 v191, 0xffff0000, v219
	v_lshlrev_b32_e32 v246, 16, v220
	v_and_b32_e32 v247, 0xffff0000, v220
	v_lshlrev_b32_e32 v248, 16, v221
	v_and_b32_e32 v249, 0xffff0000, v221
	v_pk_fma_f32 v[36:37], v[36:37], v[76:77], v[188:189]
	v_pk_fma_f32 v[38:39], v[38:39], v[78:79], v[190:191]
	v_pk_fma_f32 v[32:33], v[32:33], v[72:73], v[246:247]
	v_pk_fma_f32 v[34:35], v[34:35], v[74:75], v[248:249]
	v_cvt_pk_bf16_f32 v36, v36, v37
	v_cvt_pk_bf16_f32 v37, v38, v39
	v_cvt_pk_bf16_f32 v38, v32, v33
	v_cvt_pk_bf16_f32 v39, v34, v35
	global_store_dwordx4 v[192:193], v[36:39], off offset:256
	s_waitcnt vmcnt(12)
	v_lshlrev_b32_e32 v188, 16, v222
	v_and_b32_e32 v189, 0xffff0000, v222
	v_lshlrev_b32_e32 v190, 16, v223
	v_and_b32_e32 v191, 0xffff0000, v223
	v_lshlrev_b32_e32 v246, 16, v224
	v_and_b32_e32 v247, 0xffff0000, v224
	v_lshlrev_b32_e32 v248, 16, v225
	v_and_b32_e32 v249, 0xffff0000, v225
	v_lshl_add_u64 v[150:151], v[180:181], 1, v[144:145]
	v_pk_fma_f32 v[28:29], v[28:29], v[92:93], v[188:189]
	v_pk_fma_f32 v[30:31], v[30:31], v[94:95], v[190:191]
	v_pk_fma_f32 v[24:25], v[24:25], v[84:85], v[246:247]
	v_pk_fma_f32 v[26:27], v[26:27], v[86:87], v[248:249]
	v_cvt_pk_bf16_f32 v28, v28, v29
	v_cvt_pk_bf16_f32 v29, v30, v31
	v_cvt_pk_bf16_f32 v30, v24, v25
	v_cvt_pk_bf16_f32 v31, v26, v27
	global_store_dwordx4 v[150:151], v[28:31], off
	s_waitcnt vmcnt(11)
	v_lshlrev_b32_e32 v188, 16, v226
	v_and_b32_e32 v189, 0xffff0000, v226
	v_lshlrev_b32_e32 v190, 16, v227
	v_and_b32_e32 v191, 0xffff0000, v227
	v_lshlrev_b32_e32 v246, 16, v228
	v_and_b32_e32 v247, 0xffff0000, v228
	v_lshlrev_b32_e32 v248, 16, v229
	v_and_b32_e32 v249, 0xffff0000, v229
	v_pk_fma_f32 v[20:21], v[20:21], v[76:77], v[188:189]
	v_pk_fma_f32 v[22:23], v[22:23], v[78:79], v[190:191]
	v_pk_fma_f32 v[16:17], v[16:17], v[72:73], v[246:247]
	v_pk_fma_f32 v[18:19], v[18:19], v[74:75], v[248:249]
	v_cvt_pk_bf16_f32 v20, v20, v21
	v_cvt_pk_bf16_f32 v21, v22, v23
	v_cvt_pk_bf16_f32 v22, v16, v17
	v_cvt_pk_bf16_f32 v23, v18, v19
	global_store_dwordx4 v[150:151], v[20:23], off offset:256
	s_waitcnt vmcnt(10)
	v_lshlrev_b32_e32 v188, 16, v230
	v_and_b32_e32 v189, 0xffff0000, v230
	v_lshlrev_b32_e32 v190, 16, v231
	v_and_b32_e32 v191, 0xffff0000, v231
	v_lshlrev_b32_e32 v246, 16, v232
	v_and_b32_e32 v247, 0xffff0000, v232
	v_lshlrev_b32_e32 v248, 16, v233
	v_and_b32_e32 v249, 0xffff0000, v233
	v_lshl_add_u64 v[192:193], v[182:183], 1, v[144:145]
	v_pk_fma_f32 v[12:13], v[12:13], v[92:93], v[188:189]
	v_pk_fma_f32 v[14:15], v[14:15], v[94:95], v[190:191]
	v_pk_fma_f32 v[8:9], v[8:9], v[84:85], v[246:247]
	v_pk_fma_f32 v[10:11], v[10:11], v[86:87], v[248:249]
	v_cvt_pk_bf16_f32 v12, v12, v13
	v_cvt_pk_bf16_f32 v13, v14, v15
	v_cvt_pk_bf16_f32 v14, v8, v9
	v_cvt_pk_bf16_f32 v15, v10, v11
	global_store_dwordx4 v[192:193], v[12:15], off
	s_waitcnt vmcnt(9)
	v_lshlrev_b32_e32 v188, 16, v234
	v_and_b32_e32 v189, 0xffff0000, v234
	v_lshlrev_b32_e32 v190, 16, v235
	v_and_b32_e32 v191, 0xffff0000, v235
	v_lshlrev_b32_e32 v246, 16, v236
	v_and_b32_e32 v247, 0xffff0000, v236
	v_lshlrev_b32_e32 v248, 16, v237
	v_and_b32_e32 v249, 0xffff0000, v237
	v_pk_fma_f32 v[4:5], v[4:5], v[76:77], v[188:189]
	v_pk_fma_f32 v[6:7], v[6:7], v[78:79], v[190:191]
	v_pk_fma_f32 v[0:1], v[0:1], v[72:73], v[246:247]
	v_pk_fma_f32 v[2:3], v[2:3], v[74:75], v[248:249]
	v_cvt_pk_bf16_f32 v4, v4, v5
	v_cvt_pk_bf16_f32 v5, v6, v7
	v_cvt_pk_bf16_f32 v6, v0, v1
	v_cvt_pk_bf16_f32 v7, v2, v3
	global_store_dwordx4 v[192:193], v[4:7], off offset:256
	s_branch .Lwo_epi_done

.LBB0_773:
	s_add_u32 s22, s20, 0xfff80080
	s_addc_u32 s23, s21, -1
	s_add_i32 s61, 0, 0x10000
	ds_read_b128 v[144:147], v230
	ds_read_b128 v[148:151], v230 offset:1024
	ds_read_b128 v[162:165], v230 offset:2048
	ds_read_b128 v[166:169], v230 offset:3072
	s_cmp_eq_u32 s60, 28
	s_cselect_b32 s47, s35, s23
	s_cselect_b32 s46, s56, s22
	s_cselect_b32 s23, s25, s59
	s_cselect_b32 s22, s57, s58
	s_add_i32 m0, s5, 0xc000
	ds_read_b128 v[170:173], v143
	ds_read_b128 v[174:177], v143 offset:1024
	ds_read_b128 v[178:181], v143 offset:2048
	ds_read_b128 v[182:185], v143 offset:3072
	ds_read_b128 v[186:189], v143 offset:4096
	ds_read_b128 v[190:193], v143 offset:5120
	ds_read_b128 v[206:209], v143 offset:6144
	ds_read_b128 v[210:213], v143 offset:7168
	global_load_lds_dwordx4 v134, s[20:21]
	s_add_i32 m0, s5, 0xe000
	s_nop 0
	global_load_lds_dwordx4 v136, s[20:21]
	s_waitcnt lgkmcnt(8)
	s_barrier
	s_waitcnt lgkmcnt(0)
	v_mfma_f32_16x16x32_bf16 v[124:127], v[144:147], v[170:173], v[124:127]
	v_mfma_f32_16x16x32_bf16 v[120:123], v[162:165], v[170:173], v[120:123]
	v_mfma_f32_16x16x32_bf16 v[108:111], v[144:147], v[178:181], v[108:111]
	v_mfma_f32_16x16x32_bf16 v[104:107], v[162:165], v[178:181], v[104:107]
	v_mfma_f32_16x16x32_bf16 v[92:95], v[144:147], v[186:189], v[92:95]
	v_mfma_f32_16x16x32_bf16 v[88:91], v[162:165], v[186:189], v[88:91]
	v_mfma_f32_16x16x32_bf16 v[76:79], v[144:147], v[206:209], v[76:79]
	v_mfma_f32_16x16x32_bf16 v[72:75], v[162:165], v[206:209], v[72:75]
	v_mfma_f32_16x16x32_bf16 v[124:127], v[148:151], v[174:177], v[124:127]
	v_mfma_f32_16x16x32_bf16 v[120:123], v[166:169], v[174:177], v[120:123]
	v_mfma_f32_16x16x32_bf16 v[108:111], v[148:151], v[182:185], v[108:111]
	v_mfma_f32_16x16x32_bf16 v[104:107], v[166:169], v[182:185], v[104:107]
	v_mfma_f32_16x16x32_bf16 v[92:95], v[148:151], v[190:193], v[92:95]
	v_mfma_f32_16x16x32_bf16 v[88:91], v[166:169], v[190:193], v[88:91]
	v_mfma_f32_16x16x32_bf16 v[76:79], v[148:151], v[210:213], v[76:79]
	v_mfma_f32_16x16x32_bf16 v[72:75], v[166:169], v[210:213], v[72:75]
	s_barrier
	s_add_i32 s68, 0, 0x14000
	s_add_i32 s61, s61, s4
	ds_read_b128 v[214:217], v231
	ds_read_b128 v[218:221], v231 offset:1024
	ds_read_b128 v[222:225], v231 offset:2048
	ds_read_b128 v[226:229], v231 offset:3072
	s_mov_b32 m0, s61
	s_nop 0
	global_load_lds_dwordx4 v152, s[22:23]
	s_add_i32 m0, s61, 0x2000
	s_nop 0
	global_load_lds_dwordx4 v132, s[22:23]
	s_barrier
	s_waitcnt lgkmcnt(0)
	v_mfma_f32_16x16x32_bf16 v[116:119], v[214:217], v[170:173], v[116:119]
	v_mfma_f32_16x16x32_bf16 v[112:115], v[222:225], v[170:173], v[112:115]
	v_mfma_f32_16x16x32_bf16 v[100:103], v[214:217], v[178:181], v[100:103]
	v_mfma_f32_16x16x32_bf16 v[96:99], v[222:225], v[178:181], v[96:99]
	v_mfma_f32_16x16x32_bf16 v[84:87], v[214:217], v[186:189], v[84:87]
	v_mfma_f32_16x16x32_bf16 v[80:83], v[222:225], v[186:189], v[80:83]
	v_mfma_f32_16x16x32_bf16 v[68:71], v[214:217], v[206:209], v[68:71]
	v_mfma_f32_16x16x32_bf16 v[64:67], v[222:225], v[206:209], v[64:67]
	v_mfma_f32_16x16x32_bf16 v[116:119], v[218:221], v[174:177], v[116:119]
	v_mfma_f32_16x16x32_bf16 v[112:115], v[226:229], v[174:177], v[112:115]
	v_mfma_f32_16x16x32_bf16 v[100:103], v[218:221], v[182:185], v[100:103]
	v_mfma_f32_16x16x32_bf16 v[96:99], v[226:229], v[182:185], v[96:99]
	v_mfma_f32_16x16x32_bf16 v[84:87], v[218:221], v[190:193], v[84:87]
	v_mfma_f32_16x16x32_bf16 v[80:83], v[226:229], v[190:193], v[80:83]
	v_mfma_f32_16x16x32_bf16 v[68:71], v[218:221], v[210:213], v[68:71]
	v_mfma_f32_16x16x32_bf16 v[64:67], v[226:229], v[210:213], v[64:67]
	s_mov_b32 m0, s5
	s_add_u32 s98, s46, 0x80
	s_addc_u32 s99, s47, 0
	s_barrier
	ds_read_b128 v[170:173], v143 offset:16384
	ds_read_b128 v[174:177], v143 offset:17408
	ds_read_b128 v[178:181], v143 offset:18432
	ds_read_b128 v[182:185], v143 offset:19456
	ds_read_b128 v[186:189], v143 offset:20480
	ds_read_b128 v[190:193], v143 offset:21504
	ds_read_b128 v[206:209], v143 offset:22528
	ds_read_b128 v[210:213], v143 offset:23552
	global_load_lds_dwordx4 v128, s[46:47]
	s_mov_b32 m0, s50
	s_nop 0
	global_load_lds_dwordx4 v130, s[46:47]
	s_barrier
	s_waitcnt lgkmcnt(0)
	v_mfma_f32_16x16x32_bf16 v[60:63], v[144:147], v[170:173], v[60:63]
	v_mfma_f32_16x16x32_bf16 v[56:59], v[162:165], v[170:173], v[56:59]
	v_mfma_f32_16x16x32_bf16 v[44:47], v[144:147], v[178:181], v[44:47]
	v_mfma_f32_16x16x32_bf16 v[40:43], v[162:165], v[178:181], v[40:43]
	v_mfma_f32_16x16x32_bf16 v[28:31], v[144:147], v[186:189], v[28:31]
	v_mfma_f32_16x16x32_bf16 v[24:27], v[162:165], v[186:189], v[24:27]
	v_mfma_f32_16x16x32_bf16 v[12:15], v[144:147], v[206:209], v[12:15]
	v_mfma_f32_16x16x32_bf16 v[8:11], v[162:165], v[206:209], v[8:11]
	v_mfma_f32_16x16x32_bf16 v[60:63], v[148:151], v[174:177], v[60:63]
	v_mfma_f32_16x16x32_bf16 v[56:59], v[166:169], v[174:177], v[56:59]
	v_mfma_f32_16x16x32_bf16 v[44:47], v[148:151], v[182:185], v[44:47]
	v_mfma_f32_16x16x32_bf16 v[40:43], v[166:169], v[182:185], v[40:43]
	v_mfma_f32_16x16x32_bf16 v[28:31], v[148:151], v[190:193], v[28:31]
	v_mfma_f32_16x16x32_bf16 v[24:27], v[166:169], v[190:193], v[24:27]
	v_mfma_f32_16x16x32_bf16 v[12:15], v[148:151], v[210:213], v[12:15]
	v_mfma_f32_16x16x32_bf16 v[8:11], v[166:169], v[210:213], v[8:11]
	s_barrier
	s_add_u32 s62, s22, 0x80000
	s_addc_u32 s63, s23, 0
	s_add_i32 s61, s68, s4
	s_mov_b32 m0, s61
	s_nop 0
	global_load_lds_dwordx4 v152, s[62:63]
	s_add_i32 m0, s61, 0x2000
	s_nop 0
	global_load_lds_dwordx4 v132, s[62:63]
	s_waitcnt vmcnt(6)
	s_barrier
	v_mfma_f32_16x16x32_bf16 v[52:55], v[214:217], v[170:173], v[52:55]
	v_mfma_f32_16x16x32_bf16 v[48:51], v[222:225], v[170:173], v[48:51]
	v_mfma_f32_16x16x32_bf16 v[36:39], v[214:217], v[178:181], v[36:39]
	v_mfma_f32_16x16x32_bf16 v[32:35], v[222:225], v[178:181], v[32:35]
	v_mfma_f32_16x16x32_bf16 v[20:23], v[214:217], v[186:189], v[20:23]
	v_mfma_f32_16x16x32_bf16 v[16:19], v[222:225], v[186:189], v[16:19]
	v_mfma_f32_16x16x32_bf16 v[4:7], v[214:217], v[206:209], v[4:7]
	v_mfma_f32_16x16x32_bf16 v[0:3], v[222:225], v[206:209], v[0:3]
	v_mfma_f32_16x16x32_bf16 v[52:55], v[218:221], v[174:177], v[52:55]
	v_mfma_f32_16x16x32_bf16 v[48:51], v[226:229], v[174:177], v[48:51]
	v_mfma_f32_16x16x32_bf16 v[36:39], v[218:221], v[182:185], v[36:39]
	v_mfma_f32_16x16x32_bf16 v[32:35], v[226:229], v[182:185], v[32:35]
	v_mfma_f32_16x16x32_bf16 v[20:23], v[218:221], v[190:193], v[20:23]
	v_mfma_f32_16x16x32_bf16 v[16:19], v[226:229], v[190:193], v[16:19]
	v_mfma_f32_16x16x32_bf16 v[4:7], v[218:221], v[210:213], v[4:7]
	v_mfma_f32_16x16x32_bf16 v[0:3], v[226:229], v[210:213], v[0:3]
	s_add_i32 s61, 0, 0x18000
	s_barrier
	ds_read_b128 v[144:147], v232
	ds_read_b128 v[148:151], v232 offset:1024
	ds_read_b128 v[162:165], v232 offset:2048
	ds_read_b128 v[166:169], v232 offset:3072
	s_add_u32 s46, s46, 0x80000
	s_addc_u32 s47, s47, 0
	s_mov_b32 m0, s51
	ds_read_b128 v[170:173], v143 offset:32768
	ds_read_b128 v[174:177], v143 offset:33792
	ds_read_b128 v[178:181], v143 offset:34816
	ds_read_b128 v[182:185], v143 offset:35840
	ds_read_b128 v[186:189], v143 offset:36864
	ds_read_b128 v[190:193], v143 offset:37888
	ds_read_b128 v[206:209], v143 offset:38912
	ds_read_b128 v[210:213], v143 offset:39936
	global_load_lds_dwordx4 v128, s[46:47]
	s_mov_b32 m0, s52
	s_nop 0
	global_load_lds_dwordx4 v130, s[46:47]
	s_waitcnt lgkmcnt(8)
	s_barrier
	s_waitcnt lgkmcnt(0)
	v_mfma_f32_16x16x32_bf16 v[124:127], v[144:147], v[170:173], v[124:127]
	v_mfma_f32_16x16x32_bf16 v[120:123], v[162:165], v[170:173], v[120:123]
	v_mfma_f32_16x16x32_bf16 v[108:111], v[144:147], v[178:181], v[108:111]
	v_mfma_f32_16x16x32_bf16 v[104:107], v[162:165], v[178:181], v[104:107]
	v_mfma_f32_16x16x32_bf16 v[92:95], v[144:147], v[186:189], v[92:95]
	v_mfma_f32_16x16x32_bf16 v[88:91], v[162:165], v[186:189], v[88:91]
	v_mfma_f32_16x16x32_bf16 v[76:79], v[144:147], v[206:209], v[76:79]
	v_mfma_f32_16x16x32_bf16 v[72:75], v[162:165], v[206:209], v[72:75]
	v_mfma_f32_16x16x32_bf16 v[124:127], v[148:151], v[174:177], v[124:127]
	v_mfma_f32_16x16x32_bf16 v[120:123], v[166:169], v[174:177], v[120:123]
	v_mfma_f32_16x16x32_bf16 v[108:111], v[148:151], v[182:185], v[108:111]
	v_mfma_f32_16x16x32_bf16 v[104:107], v[166:169], v[182:185], v[104:107]
	v_mfma_f32_16x16x32_bf16 v[92:95], v[148:151], v[190:193], v[92:95]
	v_mfma_f32_16x16x32_bf16 v[88:91], v[166:169], v[190:193], v[88:91]
	v_mfma_f32_16x16x32_bf16 v[76:79], v[148:151], v[210:213], v[76:79]
	v_mfma_f32_16x16x32_bf16 v[72:75], v[166:169], v[210:213], v[72:75]
	s_barrier
	s_add_i32 s46, 0, 0x1c000
	s_add_i32 s47, s61, s4
	s_add_u32 s100, s22, 0x80
	s_addc_u32 s101, s23, 0
	s_mov_b32 m0, s47
	ds_read_b128 v[214:217], v233
	ds_read_b128 v[218:221], v233 offset:1024
	ds_read_b128 v[222:225], v233 offset:2048
	ds_read_b128 v[226:229], v233 offset:3072
	global_load_lds_dwordx4 v152, s[100:101]
	s_add_i32 m0, s47, 0x2000
	s_nop 0
	global_load_lds_dwordx4 v132, s[100:101]
	s_barrier
	s_waitcnt lgkmcnt(0)
	v_mfma_f32_16x16x32_bf16 v[116:119], v[214:217], v[170:173], v[116:119]
	v_mfma_f32_16x16x32_bf16 v[112:115], v[222:225], v[170:173], v[112:115]
	v_mfma_f32_16x16x32_bf16 v[100:103], v[214:217], v[178:181], v[100:103]
	v_mfma_f32_16x16x32_bf16 v[96:99], v[222:225], v[178:181], v[96:99]
	v_mfma_f32_16x16x32_bf16 v[84:87], v[214:217], v[186:189], v[84:87]
	v_mfma_f32_16x16x32_bf16 v[80:83], v[222:225], v[186:189], v[80:83]
	v_mfma_f32_16x16x32_bf16 v[68:71], v[214:217], v[206:209], v[68:71]
	v_mfma_f32_16x16x32_bf16 v[64:67], v[222:225], v[206:209], v[64:67]
	v_mfma_f32_16x16x32_bf16 v[116:119], v[218:221], v[174:177], v[116:119]
	v_mfma_f32_16x16x32_bf16 v[112:115], v[226:229], v[174:177], v[112:115]
	v_mfma_f32_16x16x32_bf16 v[100:103], v[218:221], v[182:185], v[100:103]
	v_mfma_f32_16x16x32_bf16 v[96:99], v[226:229], v[182:185], v[96:99]
	v_mfma_f32_16x16x32_bf16 v[84:87], v[218:221], v[190:193], v[84:87]
	v_mfma_f32_16x16x32_bf16 v[80:83], v[226:229], v[190:193], v[80:83]
	v_mfma_f32_16x16x32_bf16 v[68:71], v[218:221], v[210:213], v[68:71]
	v_mfma_f32_16x16x32_bf16 v[64:67], v[226:229], v[210:213], v[64:67]
	s_mov_b32 m0, s53
	s_barrier
	ds_read_b128 v[170:173], v143 offset:49152
	ds_read_b128 v[174:177], v143 offset:50176
	ds_read_b128 v[178:181], v143 offset:51200
	ds_read_b128 v[182:185], v143 offset:52224
	ds_read_b128 v[186:189], v143 offset:53248
	ds_read_b128 v[190:193], v143 offset:54272
	ds_read_b128 v[206:209], v143 offset:55296
	ds_read_b128 v[210:213], v143 offset:56320
	global_load_lds_dwordx4 v128, s[98:99]
	s_mov_b32 m0, s54
	s_nop 0
	global_load_lds_dwordx4 v130, s[98:99]
	s_barrier
	s_waitcnt lgkmcnt(0)
	v_mfma_f32_16x16x32_bf16 v[60:63], v[144:147], v[170:173], v[60:63]
	v_mfma_f32_16x16x32_bf16 v[56:59], v[162:165], v[170:173], v[56:59]
	v_mfma_f32_16x16x32_bf16 v[44:47], v[144:147], v[178:181], v[44:47]
	v_mfma_f32_16x16x32_bf16 v[40:43], v[162:165], v[178:181], v[40:43]
	v_mfma_f32_16x16x32_bf16 v[28:31], v[144:147], v[186:189], v[28:31]
	v_mfma_f32_16x16x32_bf16 v[24:27], v[162:165], v[186:189], v[24:27]
	v_mfma_f32_16x16x32_bf16 v[12:15], v[144:147], v[206:209], v[12:15]
	v_mfma_f32_16x16x32_bf16 v[8:11], v[162:165], v[206:209], v[8:11]
	v_mfma_f32_16x16x32_bf16 v[60:63], v[148:151], v[174:177], v[60:63]
	v_mfma_f32_16x16x32_bf16 v[56:59], v[166:169], v[174:177], v[56:59]
	v_mfma_f32_16x16x32_bf16 v[44:47], v[148:151], v[182:185], v[44:47]
	v_mfma_f32_16x16x32_bf16 v[40:43], v[166:169], v[182:185], v[40:43]
	v_mfma_f32_16x16x32_bf16 v[28:31], v[148:151], v[190:193], v[28:31]
	v_mfma_f32_16x16x32_bf16 v[24:27], v[166:169], v[190:193], v[24:27]
	v_mfma_f32_16x16x32_bf16 v[12:15], v[148:151], v[210:213], v[12:15]
	v_mfma_f32_16x16x32_bf16 v[8:11], v[166:169], v[210:213], v[8:11]
	s_barrier
	s_add_u32 s22, s22, 0x80080
	s_addc_u32 s23, s23, 0
	s_add_i32 s46, s46, s4
	s_mov_b32 m0, s46
	s_nop 0
	global_load_lds_dwordx4 v152, s[22:23]
	s_add_i32 m0, s46, 0x2000
	s_nop 0
	global_load_lds_dwordx4 v132, s[22:23]
	s_waitcnt vmcnt(6)
	s_barrier
	v_mfma_f32_16x16x32_bf16 v[52:55], v[214:217], v[170:173], v[52:55]
	v_mfma_f32_16x16x32_bf16 v[48:51], v[222:225], v[170:173], v[48:51]
	v_mfma_f32_16x16x32_bf16 v[36:39], v[214:217], v[178:181], v[36:39]
	v_mfma_f32_16x16x32_bf16 v[32:35], v[222:225], v[178:181], v[32:35]
	v_mfma_f32_16x16x32_bf16 v[20:23], v[214:217], v[186:189], v[20:23]
	v_mfma_f32_16x16x32_bf16 v[16:19], v[222:225], v[186:189], v[16:19]
	v_mfma_f32_16x16x32_bf16 v[4:7], v[214:217], v[206:209], v[4:7]
	v_mfma_f32_16x16x32_bf16 v[0:3], v[222:225], v[206:209], v[0:3]
	v_mfma_f32_16x16x32_bf16 v[52:55], v[218:221], v[174:177], v[52:55]
	v_mfma_f32_16x16x32_bf16 v[48:51], v[226:229], v[174:177], v[48:51]
	v_mfma_f32_16x16x32_bf16 v[36:39], v[218:221], v[182:185], v[36:39]
	v_mfma_f32_16x16x32_bf16 v[32:35], v[226:229], v[182:185], v[32:35]
	v_mfma_f32_16x16x32_bf16 v[20:23], v[218:221], v[190:193], v[20:23]
	v_mfma_f32_16x16x32_bf16 v[16:19], v[226:229], v[190:193], v[16:19]
	v_mfma_f32_16x16x32_bf16 v[4:7], v[218:221], v[210:213], v[4:7]
	v_mfma_f32_16x16x32_bf16 v[0:3], v[226:229], v[210:213], v[0:3]
	s_add_i32 s60, s60, 2
	s_add_u32 s20, s20, 0x100
	s_addc_u32 s21, s21, 0
	s_add_u32 s58, s58, 0x100
	s_addc_u32 s59, s59, 0
	s_cmp_gt_u32 s60, 29
	s_barrier
	s_cbranch_scc0 .LBB0_773
	v_lshl_add_u32 v144, s7, 8, v140
	v_max_f32_e32 v120, v120, v120
	v_ashrrev_i32_e32 v145, 31, v144
	v_max_f32_e32 v120, 0, v120
	v_max_f32_e32 v121, v121, v121
	v_max_f32_e32 v122, v122, v122
	v_lshl_or_b32 v138, s6, 8, v142
	v_lshlrev_b64 v[146:147], 14, v[144:145]
	v_mul_f32_e32 v145, v120, v120
	v_max_f32_e32 v120, v125, v125
	v_max_f32_e32 v121, 0, v121
	v_max_f32_e32 v122, 0, v122
	v_ashrrev_i32_e32 v139, 31, v138
	v_max_f32_e32 v124, v124, v124
	v_max_f32_e32 v120, 0, v120
	v_mul_f32_e32 v125, v121, v121
	v_max_f32_e32 v121, v126, v126
	v_mul_f32_e32 v126, v122, v122
	v_max_f32_e32 v122, v127, v127
	v_max_f32_e32 v123, v123, v123
	v_lshl_add_u64 v[146:147], s[16:17], 0, v[146:147]
	v_lshlrev_b64 v[148:149], 1, v[138:139]
	v_max_f32_e32 v124, 0, v124
	v_mul_f32_e32 v120, v120, v120
	v_max_f32_e32 v121, 0, v121
	v_max_f32_e32 v122, 0, v122
	v_max_f32_e32 v123, 0, v123
	v_max_f32_e32 v112, v112, v112
	v_lshl_add_u64 v[138:139], v[146:147], 0, v[148:149]
	v_mul_f32_e32 v124, v124, v124
	v_mul_f32_e32 v121, v121, v121
	v_mul_f32_e32 v122, v122, v122
	v_mul_f32_e32 v123, v123, v123
	v_cvt_pk_bf16_f32 v120, v124, v120
	v_max_f32_e32 v112, 0, v112
	v_max_f32_e32 v113, v113, v113
	v_max_f32_e32 v114, v114, v114
	v_cvt_pk_bf16_f32 v121, v121, v122
	v_cvt_pk_bf16_f32 v122, v145, v125
	v_cvt_pk_bf16_f32 v123, v126, v123
	global_store_dwordx4 v[138:139], v[120:123], off
	v_max_f32_e32 v113, 0, v113
	v_max_f32_e32 v114, 0, v114
	v_mul_f32_e32 v120, v112, v112
	v_max_f32_e32 v112, v117, v117
	v_max_f32_e32 v116, v116, v116
	v_max_f32_e32 v112, 0, v112
	v_mul_f32_e32 v117, v113, v113
	v_max_f32_e32 v113, v118, v118
	v_mul_f32_e32 v118, v114, v114
	v_max_f32_e32 v114, v119, v119
	v_max_f32_e32 v115, v115, v115
	v_max_f32_e32 v116, 0, v116
	v_mul_f32_e32 v112, v112, v112
	v_max_f32_e32 v113, 0, v113
	v_max_f32_e32 v114, 0, v114
	v_max_f32_e32 v115, 0, v115
	v_mul_f32_e32 v116, v116, v116
	v_mul_f32_e32 v113, v113, v113
	v_mul_f32_e32 v114, v114, v114
	v_mul_f32_e32 v115, v115, v115
	v_cvt_pk_bf16_f32 v112, v116, v112
	v_max_f32_e32 v104, v104, v104
	v_cvt_pk_bf16_f32 v113, v113, v114
	v_cvt_pk_bf16_f32 v114, v120, v117
	v_cvt_pk_bf16_f32 v115, v118, v115
	global_store_dwordx4 v[138:139], v[112:115], off offset:256
	v_max_f32_e32 v104, 0, v104
	v_max_f32_e32 v105, v105, v105
	v_or_b32_e32 v112, 16, v144
	v_max_f32_e32 v106, v106, v106
	v_ashrrev_i32_e32 v113, 31, v112
	v_mul_f32_e32 v114, v104, v104
	v_max_f32_e32 v104, v109, v109
	v_max_f32_e32 v105, 0, v105
	v_max_f32_e32 v106, 0, v106
	v_lshlrev_b64 v[112:113], 14, v[112:113]
	v_max_f32_e32 v108, v108, v108
	v_max_f32_e32 v104, 0, v104
	v_mul_f32_e32 v109, v105, v105
	v_max_f32_e32 v105, v110, v110
	v_mul_f32_e32 v110, v106, v106
	v_max_f32_e32 v106, v111, v111
	v_max_f32_e32 v107, v107, v107
	v_lshl_add_u64 v[112:113], s[16:17], 0, v[112:113]
	v_max_f32_e32 v108, 0, v108
	v_mul_f32_e32 v104, v104, v104
	v_max_f32_e32 v105, 0, v105
	v_max_f32_e32 v106, 0, v106
	v_max_f32_e32 v107, 0, v107
	v_max_f32_e32 v96, v96, v96
	v_lshl_add_u64 v[112:113], v[112:113], 0, v[148:149]
	v_mul_f32_e32 v108, v108, v108
	v_mul_f32_e32 v105, v105, v105
	v_mul_f32_e32 v106, v106, v106
	v_mul_f32_e32 v107, v107, v107
	v_cvt_pk_bf16_f32 v104, v108, v104
	v_max_f32_e32 v96, 0, v96
	v_max_f32_e32 v97, v97, v97
	v_max_f32_e32 v98, v98, v98
	v_cvt_pk_bf16_f32 v105, v105, v106
	v_cvt_pk_bf16_f32 v106, v114, v109
	v_cvt_pk_bf16_f32 v107, v110, v107
	global_store_dwordx4 v[112:113], v[104:107], off
	v_max_f32_e32 v97, 0, v97
	v_max_f32_e32 v98, 0, v98
	v_mul_f32_e32 v104, v96, v96
	v_max_f32_e32 v96, v101, v101
	v_max_f32_e32 v100, v100, v100
	v_max_f32_e32 v96, 0, v96
	v_mul_f32_e32 v101, v97, v97
	v_max_f32_e32 v97, v102, v102
	v_mul_f32_e32 v102, v98, v98
	v_max_f32_e32 v98, v103, v103
	v_max_f32_e32 v99, v99, v99
	v_max_f32_e32 v100, 0, v100
	v_mul_f32_e32 v96, v96, v96
	v_max_f32_e32 v97, 0, v97
	v_max_f32_e32 v98, 0, v98
	v_max_f32_e32 v99, 0, v99
	v_mul_f32_e32 v100, v100, v100
	v_mul_f32_e32 v97, v97, v97
	v_mul_f32_e32 v98, v98, v98
	v_mul_f32_e32 v99, v99, v99
	v_cvt_pk_bf16_f32 v96, v100, v96
	v_max_f32_e32 v88, v88, v88
	v_cvt_pk_bf16_f32 v97, v97, v98
	v_cvt_pk_bf16_f32 v98, v104, v101
	v_cvt_pk_bf16_f32 v99, v102, v99
	global_store_dwordx4 v[112:113], v[96:99], off offset:256
	v_max_f32_e32 v88, 0, v88
	v_max_f32_e32 v89, v89, v89
	v_or_b32_e32 v96, 32, v144
	v_max_f32_e32 v90, v90, v90
	v_ashrrev_i32_e32 v97, 31, v96
	v_mul_f32_e32 v98, v88, v88
	v_max_f32_e32 v88, v93, v93
	v_max_f32_e32 v89, 0, v89
	v_max_f32_e32 v90, 0, v90
	v_lshlrev_b64 v[96:97], 14, v[96:97]
	v_max_f32_e32 v92, v92, v92
	v_max_f32_e32 v88, 0, v88
	v_mul_f32_e32 v93, v89, v89
	v_max_f32_e32 v89, v94, v94
	v_mul_f32_e32 v94, v90, v90
	v_max_f32_e32 v90, v95, v95
	v_max_f32_e32 v91, v91, v91
	v_lshl_add_u64 v[96:97], s[16:17], 0, v[96:97]
	v_max_f32_e32 v92, 0, v92
	v_mul_f32_e32 v88, v88, v88
	v_max_f32_e32 v89, 0, v89
	v_max_f32_e32 v90, 0, v90
	v_max_f32_e32 v91, 0, v91
	v_max_f32_e32 v80, v80, v80
	v_lshl_add_u64 v[96:97], v[96:97], 0, v[148:149]
	v_mul_f32_e32 v92, v92, v92
	v_mul_f32_e32 v89, v89, v89
	v_mul_f32_e32 v90, v90, v90
	v_mul_f32_e32 v91, v91, v91
	v_cvt_pk_bf16_f32 v88, v92, v88
	v_max_f32_e32 v80, 0, v80
	v_max_f32_e32 v81, v81, v81
	v_max_f32_e32 v82, v82, v82
	v_cvt_pk_bf16_f32 v89, v89, v90
	v_cvt_pk_bf16_f32 v90, v98, v93
	v_cvt_pk_bf16_f32 v91, v94, v91
	global_store_dwordx4 v[96:97], v[88:91], off
	v_max_f32_e32 v81, 0, v81
	v_max_f32_e32 v82, 0, v82
	v_mul_f32_e32 v88, v80, v80
	v_max_f32_e32 v80, v85, v85
	v_max_f32_e32 v84, v84, v84
	v_max_f32_e32 v80, 0, v80
	v_mul_f32_e32 v85, v81, v81
	v_max_f32_e32 v81, v86, v86
	v_mul_f32_e32 v86, v82, v82
	v_max_f32_e32 v82, v87, v87
	v_max_f32_e32 v83, v83, v83
	v_max_f32_e32 v84, 0, v84
	v_mul_f32_e32 v80, v80, v80
	v_max_f32_e32 v81, 0, v81
	v_max_f32_e32 v82, 0, v82
	v_max_f32_e32 v83, 0, v83
	v_mul_f32_e32 v84, v84, v84
	v_mul_f32_e32 v81, v81, v81
	v_mul_f32_e32 v82, v82, v82
	v_mul_f32_e32 v83, v83, v83
	v_cvt_pk_bf16_f32 v80, v84, v80
	v_max_f32_e32 v72, v72, v72
	v_cvt_pk_bf16_f32 v81, v81, v82
	v_cvt_pk_bf16_f32 v82, v88, v85
	v_cvt_pk_bf16_f32 v83, v86, v83
	global_store_dwordx4 v[96:97], v[80:83], off offset:256
	v_max_f32_e32 v72, 0, v72
	v_max_f32_e32 v73, v73, v73
	v_or_b32_e32 v80, 48, v144
	v_max_f32_e32 v74, v74, v74
	v_ashrrev_i32_e32 v81, 31, v80
	v_mul_f32_e32 v82, v72, v72
	v_max_f32_e32 v72, v77, v77
	v_max_f32_e32 v73, 0, v73
	v_max_f32_e32 v74, 0, v74
	v_lshlrev_b64 v[80:81], 14, v[80:81]
	v_max_f32_e32 v76, v76, v76
	v_max_f32_e32 v72, 0, v72
	v_mul_f32_e32 v77, v73, v73
	v_max_f32_e32 v73, v78, v78
	v_mul_f32_e32 v78, v74, v74
	v_max_f32_e32 v74, v79, v79
	v_max_f32_e32 v75, v75, v75
	v_lshl_add_u64 v[80:81], s[16:17], 0, v[80:81]
	v_max_f32_e32 v76, 0, v76
	v_mul_f32_e32 v72, v72, v72
	v_max_f32_e32 v73, 0, v73
	v_max_f32_e32 v74, 0, v74
	v_max_f32_e32 v75, 0, v75
	v_max_f32_e32 v64, v64, v64
	v_max_f32_e32 v65, v65, v65
	v_max_f32_e32 v66, v66, v66
	v_lshl_add_u64 v[80:81], v[80:81], 0, v[148:149]
	v_mul_f32_e32 v76, v76, v76
	v_mul_f32_e32 v73, v73, v73
	v_mul_f32_e32 v74, v74, v74
	v_mul_f32_e32 v75, v75, v75
	v_cvt_pk_bf16_f32 v72, v76, v72
	v_max_f32_e32 v64, 0, v64
	v_max_f32_e32 v65, 0, v65
	v_max_f32_e32 v66, 0, v66
	v_cvt_pk_bf16_f32 v73, v73, v74
	v_cvt_pk_bf16_f32 v74, v82, v77
	v_cvt_pk_bf16_f32 v75, v78, v75
	global_store_dwordx4 v[80:81], v[72:75], off
	v_max_f32_e32 v68, v68, v68
	v_max_f32_e32 v67, v67, v67
	v_mul_f32_e32 v72, v64, v64
	v_max_f32_e32 v64, v69, v69
	v_mul_f32_e32 v69, v65, v65
	v_max_f32_e32 v65, v70, v70
	v_mul_f32_e32 v70, v66, v66
	v_max_f32_e32 v66, v71, v71
	v_max_f32_e32 v64, 0, v64
	v_max_f32_e32 v65, 0, v65
	v_max_f32_e32 v66, 0, v66
	v_max_f32_e32 v68, 0, v68
	v_mul_f32_e32 v64, v64, v64
	v_mul_f32_e32 v65, v65, v65
	v_max_f32_e32 v67, 0, v67
	v_mul_f32_e32 v66, v66, v66
	v_max_f32_e32 v56, v56, v56
	v_mul_f32_e32 v68, v68, v68
	v_mul_f32_e32 v67, v67, v67
	v_cvt_pk_bf16_f32 v64, v68, v64
	v_cvt_pk_bf16_f32 v65, v65, v66
	v_cvt_pk_bf16_f32 v66, v72, v69
	v_max_f32_e32 v56, 0, v56
	v_max_f32_e32 v57, v57, v57
	v_max_f32_e32 v58, v58, v58
	v_cvt_pk_bf16_f32 v67, v70, v67
	global_store_dwordx4 v[80:81], v[64:67], off offset:256
	v_max_f32_e32 v60, v60, v60
	v_max_f32_e32 v57, 0, v57
	v_mul_f32_e32 v66, v56, v56
	v_max_f32_e32 v56, v61, v61
	v_max_f32_e32 v58, 0, v58
	s_mov_b64 s[6:7], 0x200000
	v_max_f32_e32 v60, 0, v60
	v_max_f32_e32 v56, 0, v56
	v_mul_f32_e32 v61, v57, v57
	v_max_f32_e32 v57, v62, v62
	v_mul_f32_e32 v62, v58, v58
	v_max_f32_e32 v58, v63, v63
	v_lshl_add_u64 v[64:65], v[138:139], 0, s[6:7]
	v_mul_f32_e32 v60, v60, v60
	v_mul_f32_e32 v56, v56, v56
	v_max_f32_e32 v57, 0, v57
	v_max_f32_e32 v58, 0, v58
	v_max_f32_e32 v59, v59, v59
	s_mov_b32 s6, 0x200000
	v_mul_f32_e32 v57, v57, v57
	v_max_f32_e32 v59, 0, v59
	v_mul_f32_e32 v58, v58, v58
	v_cvt_pk_bf16_f32 v56, v60, v56
	v_add_co_u32_e32 v60, vcc, s6, v138
	v_max_f32_e32 v48, v48, v48
	v_max_f32_e32 v49, v49, v49
	v_max_f32_e32 v50, v50, v50
	v_mul_f32_e32 v59, v59, v59
	v_cvt_pk_bf16_f32 v57, v57, v58
	v_cvt_pk_bf16_f32 v58, v66, v61
	v_addc_co_u32_e32 v61, vcc, 0, v139, vcc
	v_max_f32_e32 v48, 0, v48
	v_max_f32_e32 v49, 0, v49
	v_max_f32_e32 v50, 0, v50
	v_cvt_pk_bf16_f32 v59, v62, v59
	global_store_dwordx4 v[60:61], v[56:59], off
	v_max_f32_e32 v52, v52, v52
	v_max_f32_e32 v51, v51, v51
	v_mul_f32_e32 v56, v48, v48
	v_max_f32_e32 v48, v53, v53
	v_mul_f32_e32 v53, v49, v49
	v_max_f32_e32 v49, v54, v54
	v_mul_f32_e32 v54, v50, v50
	v_max_f32_e32 v50, v55, v55
	v_max_f32_e32 v48, 0, v48
	v_max_f32_e32 v49, 0, v49
	v_max_f32_e32 v50, 0, v50
	v_max_f32_e32 v52, 0, v52
	v_mul_f32_e32 v48, v48, v48
	v_mul_f32_e32 v49, v49, v49
	v_max_f32_e32 v51, 0, v51
	v_mul_f32_e32 v50, v50, v50
	v_max_f32_e32 v40, v40, v40
	v_mul_f32_e32 v52, v52, v52
	v_mul_f32_e32 v51, v51, v51
	v_cvt_pk_bf16_f32 v48, v52, v48
	v_cvt_pk_bf16_f32 v49, v49, v50
	v_cvt_pk_bf16_f32 v50, v56, v53
	v_max_f32_e32 v40, 0, v40
	v_max_f32_e32 v41, v41, v41
	v_max_f32_e32 v42, v42, v42
	v_cvt_pk_bf16_f32 v51, v54, v51
	global_store_dwordx4 v[64:65], v[48:51], off offset:256
	v_max_f32_e32 v44, v44, v44
	v_max_f32_e32 v41, 0, v41
	v_mul_f32_e32 v50, v40, v40
	v_max_f32_e32 v40, v45, v45
	v_max_f32_e32 v42, 0, v42
	s_mov_b64 s[6:7], 0x240000
	v_max_f32_e32 v44, 0, v44
	v_max_f32_e32 v40, 0, v40
	v_mul_f32_e32 v45, v41, v41
	v_max_f32_e32 v41, v46, v46
	v_mul_f32_e32 v46, v42, v42
	v_max_f32_e32 v42, v47, v47
	v_lshl_add_u64 v[48:49], v[138:139], 0, s[6:7]
	v_mul_f32_e32 v44, v44, v44
	v_mul_f32_e32 v40, v40, v40
	v_max_f32_e32 v41, 0, v41
	v_max_f32_e32 v42, 0, v42
	v_max_f32_e32 v43, v43, v43
	s_mov_b32 s6, 0x240000
	v_mul_f32_e32 v41, v41, v41
	v_max_f32_e32 v43, 0, v43
	v_mul_f32_e32 v42, v42, v42
	v_cvt_pk_bf16_f32 v40, v44, v40
	v_add_co_u32_e32 v44, vcc, s6, v138
	v_max_f32_e32 v32, v32, v32
	v_max_f32_e32 v33, v33, v33
	v_max_f32_e32 v34, v34, v34
	v_mul_f32_e32 v43, v43, v43
	v_cvt_pk_bf16_f32 v41, v41, v42
	v_cvt_pk_bf16_f32 v42, v50, v45
	v_addc_co_u32_e32 v45, vcc, 0, v139, vcc
	v_max_f32_e32 v32, 0, v32
	v_max_f32_e32 v33, 0, v33
	v_max_f32_e32 v34, 0, v34
	v_cvt_pk_bf16_f32 v43, v46, v43
	global_store_dwordx4 v[44:45], v[40:43], off
	v_max_f32_e32 v36, v36, v36
	v_max_f32_e32 v35, v35, v35
	v_mul_f32_e32 v40, v32, v32
	v_max_f32_e32 v32, v37, v37
	v_mul_f32_e32 v37, v33, v33
	v_max_f32_e32 v33, v38, v38
	v_mul_f32_e32 v38, v34, v34
	v_max_f32_e32 v34, v39, v39
	v_max_f32_e32 v32, 0, v32
	v_max_f32_e32 v33, 0, v33
	v_max_f32_e32 v34, 0, v34
	v_max_f32_e32 v36, 0, v36
	v_mul_f32_e32 v32, v32, v32
	v_mul_f32_e32 v33, v33, v33
	v_max_f32_e32 v35, 0, v35
	v_mul_f32_e32 v34, v34, v34
	v_max_f32_e32 v24, v24, v24
	v_mul_f32_e32 v36, v36, v36
	v_mul_f32_e32 v35, v35, v35
	v_cvt_pk_bf16_f32 v32, v36, v32
	v_cvt_pk_bf16_f32 v33, v33, v34
	v_cvt_pk_bf16_f32 v34, v40, v37
	v_max_f32_e32 v24, 0, v24
	v_max_f32_e32 v25, v25, v25
	v_max_f32_e32 v26, v26, v26
	v_cvt_pk_bf16_f32 v35, v38, v35
	global_store_dwordx4 v[48:49], v[32:35], off offset:256
	v_max_f32_e32 v28, v28, v28
	v_max_f32_e32 v25, 0, v25
	v_mul_f32_e32 v34, v24, v24
	v_max_f32_e32 v24, v29, v29
	v_max_f32_e32 v26, 0, v26
	s_mov_b64 s[6:7], 0x280000
	v_max_f32_e32 v28, 0, v28
	v_max_f32_e32 v24, 0, v24
	v_mul_f32_e32 v29, v25, v25
	v_max_f32_e32 v25, v30, v30
	v_mul_f32_e32 v30, v26, v26
	v_max_f32_e32 v26, v31, v31
	v_lshl_add_u64 v[32:33], v[138:139], 0, s[6:7]
	v_mul_f32_e32 v28, v28, v28
	v_mul_f32_e32 v24, v24, v24
	v_max_f32_e32 v25, 0, v25
	v_max_f32_e32 v26, 0, v26
	v_max_f32_e32 v27, v27, v27
	s_mov_b32 s6, 0x280000
	v_mul_f32_e32 v25, v25, v25
	v_max_f32_e32 v27, 0, v27
	v_mul_f32_e32 v26, v26, v26
	v_cvt_pk_bf16_f32 v24, v28, v24
	v_add_co_u32_e32 v28, vcc, s6, v138
	v_max_f32_e32 v16, v16, v16
	v_max_f32_e32 v17, v17, v17
	v_max_f32_e32 v18, v18, v18
	v_mul_f32_e32 v27, v27, v27
	v_cvt_pk_bf16_f32 v25, v25, v26
	v_cvt_pk_bf16_f32 v26, v34, v29
	v_addc_co_u32_e32 v29, vcc, 0, v139, vcc
	v_max_f32_e32 v16, 0, v16
	v_max_f32_e32 v17, 0, v17
	v_max_f32_e32 v18, 0, v18
	v_cvt_pk_bf16_f32 v27, v30, v27
	global_store_dwordx4 v[28:29], v[24:27], off
	v_max_f32_e32 v20, v20, v20
	v_max_f32_e32 v19, v19, v19
	v_mul_f32_e32 v24, v16, v16
	v_max_f32_e32 v16, v21, v21
	v_mul_f32_e32 v21, v17, v17
	v_max_f32_e32 v17, v22, v22
	v_mul_f32_e32 v22, v18, v18
	v_max_f32_e32 v18, v23, v23
	v_max_f32_e32 v16, 0, v16
	v_max_f32_e32 v17, 0, v17
	v_max_f32_e32 v18, 0, v18
	v_max_f32_e32 v20, 0, v20
	v_mul_f32_e32 v16, v16, v16
	v_mul_f32_e32 v17, v17, v17
	v_max_f32_e32 v19, 0, v19
	v_mul_f32_e32 v18, v18, v18
	v_max_f32_e32 v8, v8, v8
	v_mul_f32_e32 v20, v20, v20
	v_mul_f32_e32 v19, v19, v19
	v_cvt_pk_bf16_f32 v16, v20, v16
	v_cvt_pk_bf16_f32 v17, v17, v18
	v_cvt_pk_bf16_f32 v18, v24, v21
	v_max_f32_e32 v8, 0, v8
	v_max_f32_e32 v9, v9, v9
	v_max_f32_e32 v10, v10, v10
	v_cvt_pk_bf16_f32 v19, v22, v19
	global_store_dwordx4 v[32:33], v[16:19], off offset:256
	v_max_f32_e32 v12, v12, v12
	v_max_f32_e32 v9, 0, v9
	v_mul_f32_e32 v18, v8, v8
	v_max_f32_e32 v8, v13, v13
	v_max_f32_e32 v10, 0, v10
	s_mov_b64 s[6:7], 0x2c0000
	v_max_f32_e32 v12, 0, v12
	v_max_f32_e32 v8, 0, v8
	v_mul_f32_e32 v13, v9, v9
	v_max_f32_e32 v9, v14, v14
	v_mul_f32_e32 v14, v10, v10
	v_max_f32_e32 v10, v15, v15
	v_lshl_add_u64 v[16:17], v[138:139], 0, s[6:7]
	v_mul_f32_e32 v12, v12, v12
	v_mul_f32_e32 v8, v8, v8
	v_max_f32_e32 v9, 0, v9
	v_max_f32_e32 v10, 0, v10
	v_max_f32_e32 v11, v11, v11
	s_mov_b32 s6, 0x2c0000
	v_mul_f32_e32 v9, v9, v9
	v_max_f32_e32 v11, 0, v11
	v_mul_f32_e32 v10, v10, v10
	v_cvt_pk_bf16_f32 v8, v12, v8
	v_add_co_u32_e32 v12, vcc, s6, v138
	v_max_f32_e32 v0, v0, v0
	v_max_f32_e32 v1, v1, v1
	v_max_f32_e32 v2, v2, v2
	v_mul_f32_e32 v11, v11, v11
	v_cvt_pk_bf16_f32 v9, v9, v10
	v_cvt_pk_bf16_f32 v10, v18, v13
	v_addc_co_u32_e32 v13, vcc, 0, v139, vcc
	v_max_f32_e32 v0, 0, v0
	v_max_f32_e32 v1, 0, v1
	v_max_f32_e32 v2, 0, v2
	v_cvt_pk_bf16_f32 v11, v14, v11
	global_store_dwordx4 v[12:13], v[8:11], off
	v_max_f32_e32 v3, v3, v3
	v_max_f32_e32 v4, v4, v4
	v_mul_f32_e32 v8, v0, v0
	v_max_f32_e32 v0, v5, v5
	v_mul_f32_e32 v5, v1, v1
	v_max_f32_e32 v1, v6, v6
	v_mul_f32_e32 v6, v2, v2
	v_max_f32_e32 v2, v7, v7
	v_max_f32_e32 v0, 0, v0
	v_max_f32_e32 v1, 0, v1
	v_max_f32_e32 v2, 0, v2
	v_max_f32_e32 v3, 0, v3
	v_max_f32_e32 v4, 0, v4
	v_mul_f32_e32 v0, v0, v0
	v_mul_f32_e32 v1, v1, v1
	v_mul_f32_e32 v2, v2, v2
	v_mul_f32_e32 v3, v3, v3
	s_and_b64 vcc, exec, s[38:39]
	s_mov_b32 s6, s24
	s_mov_b32 s7, s34
	s_mov_b64 s[22:23], s[44:45]
	s_mov_b64 s[20:21], s[42:43]
	v_mul_f32_e32 v4, v4, v4
	v_cvt_pk_bf16_f32 v0, v4, v0
	v_cvt_pk_bf16_f32 v1, v1, v2
	v_cvt_pk_bf16_f32 v2, v8, v5
	v_cvt_pk_bf16_f32 v3, v6, v3
	global_store_dwordx4 v[16:17], v[0:3], off offset:256
	s_cbranch_vccz .LBB0_770
	s_waitcnt vmcnt(0)
	v_readlane_b32 s34, v253, 45
	s_cmpk_gt_u32 s14, 0xff
	v_readlane_b32 s35, v253, 46
	s_cbranch_scc1 .LBB0_777
	s_barrier

.LBB0_836:
	s_add_u32 s22, s20, 0xffe00080
	s_addc_u32 s23, s21, -1
	s_add_i32 s78, 0, 0x10000
	ds_read_b128 v[120:123], v248
	ds_read_b128 v[124:127], v248 offset:1024
	ds_read_b128 v[132:135], v248 offset:2048
	ds_read_b128 v[136:139], v248 offset:3072
	s_cmpk_eq_i32 s69, 0x7c
	s_cselect_b32 s35, s6, s23
	s_cselect_b32 s34, s7, s22
	s_cselect_b32 s23, s1, s68
	s_cselect_b32 s22, s17, s63
	s_add_i32 m0, s52, 0xc000
	ds_read_b128 v[186:189], v185
	ds_read_b128 v[190:193], v185 offset:1024
	ds_read_b128 v[206:209], v185 offset:2048
	ds_read_b128 v[210:213], v185 offset:3072
	ds_read_b128 v[214:217], v185 offset:4096
	ds_read_b128 v[218:221], v185 offset:5120
	ds_read_b128 v[222:225], v185 offset:6144
	ds_read_b128 v[226:229], v185 offset:7168
	global_load_lds_dwordx4 v176, s[20:21]
	s_add_i32 m0, s52, 0xe000
	s_nop 0
	global_load_lds_dwordx4 v178, s[20:21]
	s_waitcnt lgkmcnt(8)
	s_barrier
	s_waitcnt lgkmcnt(0)
	v_mfma_f32_16x16x32_bf16 v[140:143], v[120:123], v[186:189], v[140:143]
	v_mfma_f32_16x16x32_bf16 v[128:131], v[132:135], v[186:189], v[128:131]
	v_mfma_f32_16x16x32_bf16 v[112:115], v[120:123], v[206:209], v[112:115]
	v_mfma_f32_16x16x32_bf16 v[104:107], v[132:135], v[206:209], v[104:107]
	v_mfma_f32_16x16x32_bf16 v[96:99], v[120:123], v[214:217], v[96:99]
	v_mfma_f32_16x16x32_bf16 v[88:91], v[132:135], v[214:217], v[88:91]
	v_mfma_f32_16x16x32_bf16 v[80:83], v[120:123], v[222:225], v[80:83]
	v_mfma_f32_16x16x32_bf16 v[72:75], v[132:135], v[222:225], v[72:75]
	v_mfma_f32_16x16x32_bf16 v[140:143], v[124:127], v[190:193], v[140:143]
	v_mfma_f32_16x16x32_bf16 v[128:131], v[136:139], v[190:193], v[128:131]
	v_mfma_f32_16x16x32_bf16 v[112:115], v[124:127], v[210:213], v[112:115]
	v_mfma_f32_16x16x32_bf16 v[104:107], v[136:139], v[210:213], v[104:107]
	v_mfma_f32_16x16x32_bf16 v[96:99], v[124:127], v[218:221], v[96:99]
	v_mfma_f32_16x16x32_bf16 v[88:91], v[136:139], v[218:221], v[88:91]
	v_mfma_f32_16x16x32_bf16 v[80:83], v[124:127], v[226:229], v[80:83]
	v_mfma_f32_16x16x32_bf16 v[72:75], v[136:139], v[226:229], v[72:75]
	s_barrier
	s_add_i32 s80, 0, 0x14000
	s_add_i32 s78, s78, s51
	ds_read_b128 v[230:233], v249
	ds_read_b128 v[234:237], v249 offset:1024
	ds_read_b128 v[238:241], v249 offset:2048
	ds_read_b128 v[242:245], v249 offset:3072
	s_mov_b32 m0, s78
	s_nop 0
	global_load_lds_dwordx4 v152, s[22:23]
	s_add_i32 m0, s78, 0x2000
	s_nop 0
	global_load_lds_dwordx4 v144, s[22:23]
	s_barrier
	s_waitcnt lgkmcnt(0)
	v_mfma_f32_16x16x32_bf16 v[116:119], v[230:233], v[186:189], v[116:119]
	v_mfma_f32_16x16x32_bf16 v[108:111], v[238:241], v[186:189], v[108:111]
	v_mfma_f32_16x16x32_bf16 v[100:103], v[230:233], v[206:209], v[100:103]
	v_mfma_f32_16x16x32_bf16 v[92:95], v[238:241], v[206:209], v[92:95]
	v_mfma_f32_16x16x32_bf16 v[84:87], v[230:233], v[214:217], v[84:87]
	v_mfma_f32_16x16x32_bf16 v[76:79], v[238:241], v[214:217], v[76:79]
	v_mfma_f32_16x16x32_bf16 v[68:71], v[230:233], v[222:225], v[68:71]
	v_mfma_f32_16x16x32_bf16 v[64:67], v[238:241], v[222:225], v[64:67]
	v_mfma_f32_16x16x32_bf16 v[116:119], v[234:237], v[190:193], v[116:119]
	v_mfma_f32_16x16x32_bf16 v[108:111], v[242:245], v[190:193], v[108:111]
	v_mfma_f32_16x16x32_bf16 v[100:103], v[234:237], v[210:213], v[100:103]
	v_mfma_f32_16x16x32_bf16 v[92:95], v[242:245], v[210:213], v[92:95]
	v_mfma_f32_16x16x32_bf16 v[84:87], v[234:237], v[218:221], v[84:87]
	v_mfma_f32_16x16x32_bf16 v[76:79], v[242:245], v[218:221], v[76:79]
	v_mfma_f32_16x16x32_bf16 v[68:71], v[234:237], v[226:229], v[68:71]
	v_mfma_f32_16x16x32_bf16 v[64:67], v[242:245], v[226:229], v[64:67]
	s_mov_b32 m0, s52
	s_add_u32 s98, s34, 0x80
	s_addc_u32 s99, s35, 0
	s_barrier
	ds_read_b128 v[186:189], v185 offset:16384
	ds_read_b128 v[190:193], v185 offset:17408
	ds_read_b128 v[206:209], v185 offset:18432
	ds_read_b128 v[210:213], v185 offset:19456
	ds_read_b128 v[214:217], v185 offset:20480
	ds_read_b128 v[218:221], v185 offset:21504
	ds_read_b128 v[222:225], v185 offset:22528
	ds_read_b128 v[226:229], v185 offset:23552
	global_load_lds_dwordx4 v148, s[34:35]
	s_mov_b32 m0, s53
	s_nop 0
	global_load_lds_dwordx4 v146, s[34:35]
	s_barrier
	s_waitcnt lgkmcnt(0)
	v_mfma_f32_16x16x32_bf16 v[60:63], v[120:123], v[186:189], v[60:63]
	v_mfma_f32_16x16x32_bf16 v[56:59], v[132:135], v[186:189], v[56:59]
	v_mfma_f32_16x16x32_bf16 v[48:51], v[120:123], v[206:209], v[48:51]
	v_mfma_f32_16x16x32_bf16 v[40:43], v[132:135], v[206:209], v[40:43]
	v_mfma_f32_16x16x32_bf16 v[32:35], v[120:123], v[214:217], v[32:35]
	v_mfma_f32_16x16x32_bf16 v[24:27], v[132:135], v[214:217], v[24:27]
	v_mfma_f32_16x16x32_bf16 v[16:19], v[120:123], v[222:225], v[16:19]
	v_mfma_f32_16x16x32_bf16 v[8:11], v[132:135], v[222:225], v[8:11]
	v_mfma_f32_16x16x32_bf16 v[60:63], v[124:127], v[190:193], v[60:63]
	v_mfma_f32_16x16x32_bf16 v[56:59], v[136:139], v[190:193], v[56:59]
	v_mfma_f32_16x16x32_bf16 v[48:51], v[124:127], v[210:213], v[48:51]
	v_mfma_f32_16x16x32_bf16 v[40:43], v[136:139], v[210:213], v[40:43]
	v_mfma_f32_16x16x32_bf16 v[32:35], v[124:127], v[218:221], v[32:35]
	v_mfma_f32_16x16x32_bf16 v[24:27], v[136:139], v[218:221], v[24:27]
	v_mfma_f32_16x16x32_bf16 v[16:19], v[124:127], v[226:229], v[16:19]
	v_mfma_f32_16x16x32_bf16 v[8:11], v[136:139], v[226:229], v[8:11]
	s_barrier
	s_add_u32 s78, s22, 0x200000
	s_addc_u32 s79, s23, 0
	s_add_i32 s80, s80, s51
	s_mov_b32 m0, s80
	s_nop 0
	global_load_lds_dwordx4 v152, s[78:79]
	s_add_i32 m0, s80, 0x2000
	s_nop 0
	global_load_lds_dwordx4 v144, s[78:79]
	s_waitcnt vmcnt(6)
	s_barrier
	v_mfma_f32_16x16x32_bf16 v[52:55], v[230:233], v[186:189], v[52:55]
	v_mfma_f32_16x16x32_bf16 v[44:47], v[238:241], v[186:189], v[44:47]
	v_mfma_f32_16x16x32_bf16 v[36:39], v[230:233], v[206:209], v[36:39]
	v_mfma_f32_16x16x32_bf16 v[28:31], v[238:241], v[206:209], v[28:31]
	v_mfma_f32_16x16x32_bf16 v[20:23], v[230:233], v[214:217], v[20:23]
	v_mfma_f32_16x16x32_bf16 v[12:15], v[238:241], v[214:217], v[12:15]
	v_mfma_f32_16x16x32_bf16 v[4:7], v[230:233], v[222:225], v[4:7]
	v_mfma_f32_16x16x32_bf16 v[0:3], v[238:241], v[222:225], v[0:3]
	v_mfma_f32_16x16x32_bf16 v[52:55], v[234:237], v[190:193], v[52:55]
	v_mfma_f32_16x16x32_bf16 v[44:47], v[242:245], v[190:193], v[44:47]
	v_mfma_f32_16x16x32_bf16 v[36:39], v[234:237], v[210:213], v[36:39]
	v_mfma_f32_16x16x32_bf16 v[28:31], v[242:245], v[210:213], v[28:31]
	v_mfma_f32_16x16x32_bf16 v[20:23], v[234:237], v[218:221], v[20:23]
	v_mfma_f32_16x16x32_bf16 v[12:15], v[242:245], v[218:221], v[12:15]
	v_mfma_f32_16x16x32_bf16 v[4:7], v[234:237], v[226:229], v[4:7]
	v_mfma_f32_16x16x32_bf16 v[0:3], v[242:245], v[226:229], v[0:3]
	s_add_i32 s78, 0, 0x18000
	s_barrier
	ds_read_b128 v[120:123], v250
	ds_read_b128 v[124:127], v250 offset:1024
	ds_read_b128 v[132:135], v250 offset:2048
	ds_read_b128 v[136:139], v250 offset:3072
	s_add_u32 s34, s34, 0x200000
	s_addc_u32 s35, s35, 0
	s_mov_b32 m0, s54
	ds_read_b128 v[186:189], v185 offset:32768
	ds_read_b128 v[190:193], v185 offset:33792
	ds_read_b128 v[206:209], v185 offset:34816
	ds_read_b128 v[210:213], v185 offset:35840
	ds_read_b128 v[214:217], v185 offset:36864
	ds_read_b128 v[218:221], v185 offset:37888
	ds_read_b128 v[222:225], v185 offset:38912
	ds_read_b128 v[226:229], v185 offset:39936
	global_load_lds_dwordx4 v148, s[34:35]
	s_mov_b32 m0, s55
	s_nop 0
	global_load_lds_dwordx4 v146, s[34:35]
	s_waitcnt lgkmcnt(8)
	s_barrier
	s_waitcnt lgkmcnt(0)
	v_mfma_f32_16x16x32_bf16 v[140:143], v[120:123], v[186:189], v[140:143]
	v_mfma_f32_16x16x32_bf16 v[128:131], v[132:135], v[186:189], v[128:131]
	v_mfma_f32_16x16x32_bf16 v[112:115], v[120:123], v[206:209], v[112:115]
	v_mfma_f32_16x16x32_bf16 v[104:107], v[132:135], v[206:209], v[104:107]
	v_mfma_f32_16x16x32_bf16 v[96:99], v[120:123], v[214:217], v[96:99]
	v_mfma_f32_16x16x32_bf16 v[88:91], v[132:135], v[214:217], v[88:91]
	v_mfma_f32_16x16x32_bf16 v[80:83], v[120:123], v[222:225], v[80:83]
	v_mfma_f32_16x16x32_bf16 v[72:75], v[132:135], v[222:225], v[72:75]
	v_mfma_f32_16x16x32_bf16 v[140:143], v[124:127], v[190:193], v[140:143]
	v_mfma_f32_16x16x32_bf16 v[128:131], v[136:139], v[190:193], v[128:131]
	v_mfma_f32_16x16x32_bf16 v[112:115], v[124:127], v[210:213], v[112:115]
	v_mfma_f32_16x16x32_bf16 v[104:107], v[136:139], v[210:213], v[104:107]
	v_mfma_f32_16x16x32_bf16 v[96:99], v[124:127], v[218:221], v[96:99]
	v_mfma_f32_16x16x32_bf16 v[88:91], v[136:139], v[218:221], v[88:91]
	v_mfma_f32_16x16x32_bf16 v[80:83], v[124:127], v[226:229], v[80:83]
	v_mfma_f32_16x16x32_bf16 v[72:75], v[136:139], v[226:229], v[72:75]
	s_barrier
	s_add_i32 s34, 0, 0x1c000
	s_add_i32 s35, s78, s51
	s_add_u32 s100, s22, 0x80
	s_addc_u32 s101, s23, 0
	s_mov_b32 m0, s35
	ds_read_b128 v[230:233], v251
	ds_read_b128 v[234:237], v251 offset:1024
	ds_read_b128 v[238:241], v251 offset:2048
	ds_read_b128 v[242:245], v251 offset:3072
	global_load_lds_dwordx4 v152, s[100:101]
	s_add_i32 m0, s35, 0x2000
	s_nop 0
	global_load_lds_dwordx4 v144, s[100:101]
	s_barrier
	s_waitcnt lgkmcnt(0)
	v_mfma_f32_16x16x32_bf16 v[116:119], v[230:233], v[186:189], v[116:119]
	v_mfma_f32_16x16x32_bf16 v[108:111], v[238:241], v[186:189], v[108:111]
	v_mfma_f32_16x16x32_bf16 v[100:103], v[230:233], v[206:209], v[100:103]
	v_mfma_f32_16x16x32_bf16 v[92:95], v[238:241], v[206:209], v[92:95]
	v_mfma_f32_16x16x32_bf16 v[84:87], v[230:233], v[214:217], v[84:87]
	v_mfma_f32_16x16x32_bf16 v[76:79], v[238:241], v[214:217], v[76:79]
	v_mfma_f32_16x16x32_bf16 v[68:71], v[230:233], v[222:225], v[68:71]
	v_mfma_f32_16x16x32_bf16 v[64:67], v[238:241], v[222:225], v[64:67]
	v_mfma_f32_16x16x32_bf16 v[116:119], v[234:237], v[190:193], v[116:119]
	v_mfma_f32_16x16x32_bf16 v[108:111], v[242:245], v[190:193], v[108:111]
	v_mfma_f32_16x16x32_bf16 v[100:103], v[234:237], v[210:213], v[100:103]
	v_mfma_f32_16x16x32_bf16 v[92:95], v[242:245], v[210:213], v[92:95]
	v_mfma_f32_16x16x32_bf16 v[84:87], v[234:237], v[218:221], v[84:87]
	v_mfma_f32_16x16x32_bf16 v[76:79], v[242:245], v[218:221], v[76:79]
	v_mfma_f32_16x16x32_bf16 v[68:71], v[234:237], v[226:229], v[68:71]
	v_mfma_f32_16x16x32_bf16 v[64:67], v[242:245], v[226:229], v[64:67]
	s_mov_b32 m0, s60
	s_barrier
	ds_read_b128 v[186:189], v185 offset:49152
	ds_read_b128 v[190:193], v185 offset:50176
	ds_read_b128 v[206:209], v185 offset:51200
	ds_read_b128 v[210:213], v185 offset:52224
	ds_read_b128 v[214:217], v185 offset:53248
	ds_read_b128 v[218:221], v185 offset:54272
	ds_read_b128 v[222:225], v185 offset:55296
	ds_read_b128 v[226:229], v185 offset:56320
	global_load_lds_dwordx4 v148, s[98:99]
	s_mov_b32 m0, s61
	s_nop 0
	global_load_lds_dwordx4 v146, s[98:99]
	s_barrier
	s_waitcnt lgkmcnt(0)
	v_mfma_f32_16x16x32_bf16 v[60:63], v[120:123], v[186:189], v[60:63]
	v_mfma_f32_16x16x32_bf16 v[56:59], v[132:135], v[186:189], v[56:59]
	v_mfma_f32_16x16x32_bf16 v[48:51], v[120:123], v[206:209], v[48:51]
	v_mfma_f32_16x16x32_bf16 v[40:43], v[132:135], v[206:209], v[40:43]
	v_mfma_f32_16x16x32_bf16 v[32:35], v[120:123], v[214:217], v[32:35]
	v_mfma_f32_16x16x32_bf16 v[24:27], v[132:135], v[214:217], v[24:27]
	v_mfma_f32_16x16x32_bf16 v[16:19], v[120:123], v[222:225], v[16:19]
	v_mfma_f32_16x16x32_bf16 v[8:11], v[132:135], v[222:225], v[8:11]
	v_mfma_f32_16x16x32_bf16 v[60:63], v[124:127], v[190:193], v[60:63]
	v_mfma_f32_16x16x32_bf16 v[56:59], v[136:139], v[190:193], v[56:59]
	v_mfma_f32_16x16x32_bf16 v[48:51], v[124:127], v[210:213], v[48:51]
	v_mfma_f32_16x16x32_bf16 v[40:43], v[136:139], v[210:213], v[40:43]
	v_mfma_f32_16x16x32_bf16 v[32:35], v[124:127], v[218:221], v[32:35]
	v_mfma_f32_16x16x32_bf16 v[24:27], v[136:139], v[218:221], v[24:27]
	v_mfma_f32_16x16x32_bf16 v[16:19], v[124:127], v[226:229], v[16:19]
	v_mfma_f32_16x16x32_bf16 v[8:11], v[136:139], v[226:229], v[8:11]
	s_barrier
	s_add_u32 s22, s22, 0x200080
	s_addc_u32 s23, s23, 0
	s_add_i32 s34, s34, s51
	s_mov_b32 m0, s34
	s_nop 0
	global_load_lds_dwordx4 v152, s[22:23]
	s_add_i32 m0, s34, 0x2000
	s_nop 0
	global_load_lds_dwordx4 v144, s[22:23]
	s_waitcnt vmcnt(6)
	s_barrier
	v_mfma_f32_16x16x32_bf16 v[52:55], v[230:233], v[186:189], v[52:55]
	v_mfma_f32_16x16x32_bf16 v[44:47], v[238:241], v[186:189], v[44:47]
	v_mfma_f32_16x16x32_bf16 v[36:39], v[230:233], v[206:209], v[36:39]
	v_mfma_f32_16x16x32_bf16 v[28:31], v[238:241], v[206:209], v[28:31]
	v_mfma_f32_16x16x32_bf16 v[20:23], v[230:233], v[214:217], v[20:23]
	v_mfma_f32_16x16x32_bf16 v[12:15], v[238:241], v[214:217], v[12:15]
	v_mfma_f32_16x16x32_bf16 v[4:7], v[230:233], v[222:225], v[4:7]
	v_mfma_f32_16x16x32_bf16 v[0:3], v[238:241], v[222:225], v[0:3]
	v_mfma_f32_16x16x32_bf16 v[52:55], v[234:237], v[190:193], v[52:55]
	v_mfma_f32_16x16x32_bf16 v[44:47], v[242:245], v[190:193], v[44:47]
	v_mfma_f32_16x16x32_bf16 v[36:39], v[234:237], v[210:213], v[36:39]
	v_mfma_f32_16x16x32_bf16 v[28:31], v[242:245], v[210:213], v[28:31]
	v_mfma_f32_16x16x32_bf16 v[20:23], v[234:237], v[218:221], v[20:23]
	v_mfma_f32_16x16x32_bf16 v[12:15], v[242:245], v[218:221], v[12:15]
	v_mfma_f32_16x16x32_bf16 v[4:7], v[234:237], v[226:229], v[4:7]
	v_mfma_f32_16x16x32_bf16 v[0:3], v[242:245], v[226:229], v[0:3]
	s_add_i32 s69, s69, 2
	s_add_u32 s20, s20, 0x100
	s_addc_u32 s21, s21, 0
	s_add_u32 s63, s63, 0x100
	s_addc_u32 s68, s68, 0
	s_cmpk_gt_u32 s69, 0x7d
	s_barrier
	s_cbranch_scc0 .LBB0_836
	v_readlane_b32 s98, v246, 0
	v_readlane_b32 s99, v246, 1
	s_cmp_eq_u32 s99, 0
	s_cbranch_scc1 .Lm2_epi
	s_and_b32 s100, s2, 0x7f
	s_lshl_b32 s100, s100, 18
	s_add_u32 s100, s100, 0x29800000
	s_add_u32 s100, s46, s100
	s_addc_u32 s101, s47, 0
	v_lshlrev_b32_e32 v186, 4, v182
	s_cmp_eq_u32 s99, 1
	s_cbranch_scc1 .Lm2_put_partial
	s_and_b32 s6, s2, 0x7f
	s_lshl_b32 s6, s6, 6
	s_add_u32 s6, s6, 0x2970a000
	s_add_u32 s6, s46, s6
	s_addc_u32 s7, s47, 0
	v_mov_b32_e32 v187, 0
	s_mov_b32 s99, 0
